# GDN conv taps staged in LDS once; RWKV S5 MFMA chains software-pipelined; P2c queue hands out HGRN items first
# speedup vs baseline: 1.0655x; 1.0048x over previous
.LBB0_540:
	v_and_b32_e32 v59, 15, v46
	v_ashrrev_i32_e32 v2, 4, v46
	v_mul_u32_u24_e32 v47, 0x90, v59
	v_lshlrev_b32_e32 v60, 3, v2
	v_add3_u32 v56, 0, v47, v60
	v_add_u32_e32 v57, 0x800, v56
	v_add_u32_e32 v58, 0x1000, v56
	v_add_u32_e32 v61, 0x1800, v56
	v_add_u32_e32 v74, 0xd800, v56
	v_add_u32_e32 v84, 0xe000, v56
	v_add_u32_e32 v250, 0xe800, v56
	v_add_u32_e32 v251, 0xf000, v56
	ds_read2_b64 v[8:11], v56 offset1:4
	ds_read2_b64 v[12:15], v57 offset0:32 offset1:36
	ds_read2_b64 v[16:19], v58 offset0:64 offset1:68
	ds_read2_b64 v[52:55], v61 offset0:96 offset1:100
	ds_read2_b64 v[62:65], v74 offset1:4
	ds_read2_b64 v[66:69], v84 offset0:32 offset1:36
	ds_read2_b64 v[70:73], v250 offset0:64 offset1:68
	ds_read2_b64 v[76:79], v251 offset0:96 offset1:100
	v_cndmask_b32_e64 v254, 0, 1, s[36:37]
	v_cmp_ne_u32_e64 s[10:11], 1, v254
	s_andn2_b64 vcc, exec, s[36:37]
	s_cbranch_vccnz .Lrw5b_short
	s_waitcnt lgkmcnt(7)
	v_mfma_f32_16x16x32_bf16 v[20:23], v[8:11], v[108:111], v[124:127]
	ds_read2_b64 v[8:11], v56 offset0:8 offset1:12
	s_waitcnt lgkmcnt(7)
	v_mfma_f32_16x16x32_bf16 v[24:27], v[12:15], v[108:111], v[128:131]
	ds_read2_b64 v[12:15], v57 offset0:40 offset1:44
	s_waitcnt lgkmcnt(7)
	v_mfma_f32_16x16x32_bf16 v[32:35], v[16:19], v[108:111], v[132:135]
	ds_read2_b64 v[16:19], v58 offset0:72 offset1:76
	s_waitcnt lgkmcnt(7)
	v_mfma_f32_16x16x32_bf16 v[36:39], v[52:55], v[108:111], v[136:139]
	ds_read2_b64 v[52:55], v61 offset0:104 offset1:108
	s_waitcnt lgkmcnt(7)
	v_mfma_f32_16x16x32_bf16 v[20:23], v[62:65], v[116:119], v[20:23]
	ds_read2_b64 v[62:65], v74 offset0:8 offset1:12
	s_waitcnt lgkmcnt(7)
	v_mfma_f32_16x16x32_bf16 v[24:27], v[66:69], v[116:119], v[24:27]
	ds_read2_b64 v[66:69], v84 offset0:40 offset1:44
	s_waitcnt lgkmcnt(7)
	v_mfma_f32_16x16x32_bf16 v[32:35], v[70:73], v[116:119], v[32:35]
	ds_read2_b64 v[70:73], v250 offset0:72 offset1:76
	s_waitcnt lgkmcnt(7)
	v_mfma_f32_16x16x32_bf16 v[36:39], v[76:79], v[116:119], v[36:39]
	ds_read2_b64 v[76:79], v251 offset0:104 offset1:108
	s_waitcnt lgkmcnt(7)
	v_mfma_f32_16x16x32_bf16 v[20:23], v[8:11], v[112:115], v[20:23]
	s_waitcnt lgkmcnt(6)
	v_mfma_f32_16x16x32_bf16 v[24:27], v[12:15], v[112:115], v[24:27]
	s_waitcnt lgkmcnt(5)
	v_mfma_f32_16x16x32_bf16 v[32:35], v[16:19], v[112:115], v[32:35]
	s_waitcnt lgkmcnt(4)
	v_mfma_f32_16x16x32_bf16 v[36:39], v[52:55], v[112:115], v[36:39]
	s_waitcnt lgkmcnt(3)
	v_mfma_f32_16x16x32_bf16 v[20:23], v[62:65], v[120:123], v[20:23]
	s_waitcnt lgkmcnt(2)
	v_mfma_f32_16x16x32_bf16 v[24:27], v[66:69], v[120:123], v[24:27]
	s_waitcnt lgkmcnt(1)
	v_mfma_f32_16x16x32_bf16 v[32:35], v[70:73], v[120:123], v[32:35]
	s_waitcnt lgkmcnt(0)
	v_mfma_f32_16x16x32_bf16 v[36:39], v[76:79], v[120:123], v[36:39]
	s_branch .Lrw5b_done
.Lrw5b_short:
	s_waitcnt lgkmcnt(7)
	v_mfma_f32_16x16x32_bf16 v[20:23], v[8:11], v[108:111], v[124:127]
	s_waitcnt lgkmcnt(6)
	v_mfma_f32_16x16x32_bf16 v[24:27], v[12:15], v[108:111], v[128:131]
	s_waitcnt lgkmcnt(5)
	v_mfma_f32_16x16x32_bf16 v[32:35], v[16:19], v[108:111], v[132:135]
	s_waitcnt lgkmcnt(4)
	v_mfma_f32_16x16x32_bf16 v[36:39], v[52:55], v[108:111], v[136:139]
	s_waitcnt lgkmcnt(3)
	v_mfma_f32_16x16x32_bf16 v[20:23], v[62:65], v[116:119], v[20:23]
	s_waitcnt lgkmcnt(2)
	v_mfma_f32_16x16x32_bf16 v[24:27], v[66:69], v[116:119], v[24:27]
	s_waitcnt lgkmcnt(1)
	v_mfma_f32_16x16x32_bf16 v[32:35], v[70:73], v[116:119], v[32:35]
	s_waitcnt lgkmcnt(0)
	v_mfma_f32_16x16x32_bf16 v[36:39], v[76:79], v[116:119], v[36:39]
.Lrw5b_done:
	s_nop 7
.LBB0_548:
	v_readlane_b32 s14, v252, 1
	v_readlane_b32 s15, v252, 2
	v_lshlrev_b32_e32 v40, 2, v2
	s_mov_b64 s[12:13], -1
	s_and_b64 vcc, exec, s[14:15]
	s_cbranch_vccz .LBB0_550
	v_add_f32_e32 v2, v20, v21
	v_add_f32_e32 v8, v22, v23
	v_add_f32_e32 v2, v2, v8
	v_add_f32_e32 v8, v24, v25
	v_add_f32_e32 v9, v26, v27
	v_add_f32_e32 v2, 0, v2
	v_add_f32_e32 v8, v8, v9
	v_add_f32_e32 v2, v2, v8
	v_add_f32_e32 v8, v32, v33
	v_add_f32_e32 v9, v34, v35
	v_add_f32_e32 v8, v8, v9
	v_add_f32_e32 v2, v2, v8
	v_mov_b32_e32 v8, v37
	v_mov_b32_e32 v9, v38
	v_mov_b32_e32 v10, v36
	v_mov_b32_e32 v11, v39
	v_pk_add_f32 v[8:9], v[8:9], v[10:11]
	s_add_i32 s12, s0, s42
	v_add_f32_e32 v8, v8, v9
	v_and_b32_e32 v9, 64, v234
	v_add_f32_e32 v2, v2, v8
	v_xor_b32_e32 v8, 16, v234
	v_add_u32_e32 v9, 64, v9
	v_cmp_lt_i32_e32 vcc, v8, v9
	v_lshlrev_b32_e32 v56, 16, v188
	v_and_b32_e32 v57, 0xffff0000, v188
	v_cndmask_b32_e32 v8, v234, v8, vcc
	v_lshlrev_b32_e32 v16, 2, v8
	ds_bpermute_b32 v8, v16, v2
	v_readlane_b32 s14, v252, 27
	v_readlane_b32 s15, v252, 28
	s_waitcnt lgkmcnt(0)
	v_add_f32_e32 v2, v2, v8
	v_xor_b32_e32 v8, 32, v234
	v_cmp_lt_i32_e32 vcc, v8, v9
	v_add_u32_e32 v44, s14, v40
	v_ashrrev_i32_e32 v45, 31, v44
	v_cndmask_b32_e32 v8, v234, v8, vcc
	v_lshlrev_b32_e32 v17, 2, v8
	ds_bpermute_b32 v8, v17, v2
	s_waitcnt lgkmcnt(0)
	v_add_f32_e32 v18, v2, v8
	v_fmamk_f32 v149, v18, 0xbc800000, v21
	v_fmamk_f32 v148, v18, 0xbc800000, v20
	v_fmamk_f32 v155, v18, 0xbc800000, v23
	v_fmamk_f32 v154, v18, 0xbc800000, v22
	v_pk_mul_f32 v[8:9], v[154:155], v[154:155]
	v_pk_mul_f32 v[10:11], v[148:149], v[148:149]
	v_fmamk_f32 v153, v18, 0xbc800000, v25
	v_pk_mov_b32 v[12:13], v[10:11], v[8:9] op_sel:[1,0]
	v_mov_b32_e32 v11, v9
	v_fmamk_f32 v152, v18, 0xbc800000, v24
	v_fmamk_f32 v151, v18, 0xbc800000, v27
	v_fmamk_f32 v150, v18, 0xbc800000, v26
	v_pk_add_f32 v[8:9], v[12:13], v[10:11]
	v_pk_mul_f32 v[10:11], v[150:151], v[150:151]
	v_pk_mul_f32 v[12:13], v[152:153], v[152:153]
	v_fmamk_f32 v172, v18, 0xbc800000, v32
	v_pk_mov_b32 v[14:15], v[12:13], v[10:11] op_sel:[1,0]
	v_mov_b32_e32 v13, v11
	v_fmamk_f32 v168, v18, 0xbc800000, v34
	v_fmamk_f32 v173, v18, 0xbc800000, v33
	v_mul_f32_e32 v2, v172, v172
	v_pk_add_f32 v[10:11], v[14:15], v[12:13]
	v_fmamk_f32 v169, v18, 0xbc800000, v35
	v_pk_fma_f32 v[12:13], v[172:173], v[172:173], v[2:3] op_sel_hi:[1,1,0]
	v_mul_f32_e32 v2, v168, v168
	v_pk_add_f32 v[8:9], v[8:9], v[8:9] op_sel_hi:[0,1]
	v_pk_add_f32 v[10:11], v[10:11], v[10:11] op_sel_hi:[0,1]
	v_pk_fma_f32 v[14:15], v[168:169], v[168:169], v[2:3] op_sel_hi:[1,1,0]
	v_fmamk_f32 v171, v18, 0xbc800000, v39
	v_fmamk_f32 v170, v18, 0xbc800000, v38
	v_fmamk_f32 v175, v18, 0xbc800000, v37
	v_fmamk_f32 v174, v18, 0xbc800000, v36
	v_mul_f32_e32 v12, v174, v174
	v_mul_f32_e32 v14, v175, v175
	v_mul_f32_e32 v8, v170, v170
	v_mul_f32_e32 v10, v171, v171
	v_pk_add_f32 v[12:13], v[12:13], v[14:15]
	v_pk_add_f32 v[8:9], v[8:9], v[10:11]
	s_nop 0
	v_pk_add_f32 v[8:9], v[12:13], v[8:9]
	s_nop 0
	v_add_f32_e32 v2, v8, v9
	ds_bpermute_b32 v8, v16, v2
	s_waitcnt lgkmcnt(0)
	v_add_f32_e32 v2, v2, v8
	ds_bpermute_b32 v8, v17, v2
	v_lshrrev_b32_e32 v17, 2, v59
	v_or_b32_e32 v41, v40, v17
	s_waitcnt lgkmcnt(0)
	v_add_f32_e32 v2, v2, v8
	v_fmamk_f32 v2, v2, 0x3c800000, v156
	v_cmp_gt_f32_e32 vcc, s75, v2
	v_mul_f32_e32 v8, 0x4b800000, v2
	s_nop 0
	v_cndmask_b32_e32 v2, v2, v8, vcc
	v_rsq_f32_e32 v2, v2
	s_nop 0
	v_mul_f32_e32 v8, 0x45800000, v2
	v_cndmask_b32_e32 v16, v2, v8, vcc
	v_add_u32_e32 v2, s12, v59
	v_readlane_b32 s12, v252, 38
	v_subrev_u32_e32 v2, 63, v2
	v_pk_mul_f32 v[66:67], v[148:149], v[16:17] op_sel_hi:[1,0]
	v_lshl_add_u32 v8, v59, 2, s12
	ds_read_b32 v18, v8
	v_lshlrev_b32_e32 v8, 3, v46
	v_and_b32_e32 v8, 24, v8
	v_add_u32_e32 v42, s55, v8
	v_lshlrev_b64 v[8:9], 11, v[2:3]
	v_readlane_b32 s12, v252, 36
	v_lshl_add_u32 v2, v40, 2, 0
	v_readlane_b32 s13, v252, 37
	v_add_u32_e32 v19, 0x27600, v2
	v_add_u32_e32 v2, 0x27700, v2
	v_lshl_add_u64 v[52:53], s[12:13], 0, v[8:9]
	ds_read_b128 v[8:11], v19
	ds_read_b128 v[12:15], v2
	v_mad_u64_u32 v[54:55], s[12:13], v41, s89, v[42:43]
	v_mul_f32_e32 v41, 0xbfb8aa3b, v56
	v_exp_f32_e32 v41, v41
	s_waitcnt lgkmcnt(0)
	v_pk_fma_f32 v[8:9], v[8:9], v[66:67], v[12:13]
	v_mul_f32_e32 v12, 0xbfb8aa3b, v57
	v_exp_f32_e32 v12, v12
	ds_read_b64_tr_b16 v[54:55], v54 offset:55296
	v_add_f32_e32 v41, 1.0, v41
	v_rcp_f32_e32 v64, v41
	v_add_f32_e32 v12, 1.0, v12
	v_rcp_f32_e32 v65, v12
	s_waitcnt lgkmcnt(0)
	v_and_b32_e32 v63, 0xffff0000, v54
	v_lshlrev_b32_e32 v62, 16, v54
	v_pk_fma_f32 v[8:9], v[18:19], v[62:63], v[8:9] op_sel_hi:[0,1,1]
	v_pk_mul_f32 v[12:13], v[64:65], v[56:57]
	v_and_b32_e32 v57, 0xffff0000, v55
	v_pk_mul_f32 v[8:9], v[12:13], v[8:9]
	v_lshlrev_b32_e32 v12, 16, v189
	v_cvt_pk_bf16_f32 v8, v8, v9
	v_mul_f32_e32 v9, 0xbfb8aa3b, v12
	v_exp_f32_e32 v9, v9
	v_and_b32_e32 v13, 0xffff0000, v189
	v_lshlrev_b32_e32 v56, 16, v55
	v_pk_mul_f32 v[62:63], v[154:155], v[16:17] op_sel_hi:[1,0]
	v_add_f32_e32 v9, 1.0, v9
	v_rcp_f32_e32 v54, v9
	v_mul_f32_e32 v9, 0xbfb8aa3b, v13
	v_exp_f32_e32 v9, v9
	v_pk_fma_f32 v[10:11], v[10:11], v[62:63], v[14:15]
	v_add_u32_e32 v17, v40, v17
	v_pk_fma_f32 v[10:11], v[18:19], v[56:57], v[10:11] op_sel_hi:[0,1,1]
	v_add_f32_e32 v9, 1.0, v9
	v_rcp_f32_e32 v55, v9
	v_ashrrev_i32_e32 v41, 31, v40
	v_pk_mul_f32 v[12:13], v[54:55], v[12:13]
	s_nop 0
	v_pk_mul_f32 v[10:11], v[12:13], v[10:11]
	v_lshlrev_b32_e32 v54, 16, v186
	v_cvt_pk_bf16_f32 v9, v10, v11
	v_lshl_add_u64 v[10:11], v[44:45], 1, v[52:53]
	v_mad_u64_u32 v[44:45], s[12:13], v17, s89, v[42:43]
	v_mul_f32_e32 v17, 0xbfb8aa3b, v54
	global_store_dwordx2 v[10:11], v[8:9], off offset:1536
	v_exp_f32_e32 v17, v17
	ds_read_b128 v[8:11], v19 offset:64
	ds_read_b128 v[12:15], v2 offset:64
	v_and_b32_e32 v55, 0xffff0000, v186
	ds_read_b64_tr_b16 v[42:43], v44 offset:57600
	v_add_f32_e32 v17, 1.0, v17
	v_pk_mul_f32 v[64:65], v[152:153], v[16:17] op_sel_hi:[1,0]
	v_rcp_f32_e32 v62, v17
	s_waitcnt lgkmcnt(0)
	v_pk_fma_f32 v[8:9], v[8:9], v[64:65], v[12:13]
	v_mul_f32_e32 v12, 0xbfb8aa3b, v55
	v_exp_f32_e32 v12, v12
	v_and_b32_e32 v57, 0xffff0000, v42
	v_lshlrev_b32_e32 v56, 16, v42
	v_pk_fma_f32 v[8:9], v[18:19], v[56:57], v[8:9] op_sel_hi:[0,1,1]
	v_add_f32_e32 v12, 1.0, v12
	v_rcp_f32_e32 v63, v12
	v_pk_mul_f32 v[56:57], v[150:151], v[16:17] op_sel_hi:[1,0]
	s_mov_b64 s[12:13], 0
	v_pk_fma_f32 v[10:11], v[10:11], v[56:57], v[14:15]
	v_pk_mul_f32 v[12:13], v[62:63], v[54:55]
	v_and_b32_e32 v55, 0xffff0000, v43
	v_pk_mul_f32 v[8:9], v[12:13], v[8:9]
	v_lshlrev_b32_e32 v12, 16, v187
	v_cvt_pk_bf16_f32 v8, v8, v9
	v_mul_f32_e32 v9, 0xbfb8aa3b, v12
	v_exp_f32_e32 v9, v9
	v_and_b32_e32 v13, 0xffff0000, v187
	v_lshlrev_b32_e32 v54, 16, v43
	v_pk_fma_f32 v[10:11], v[18:19], v[54:55], v[10:11] op_sel_hi:[0,1,1]
	v_add_f32_e32 v9, 1.0, v9
	v_rcp_f32_e32 v42, v9
	v_mul_f32_e32 v9, 0xbfb8aa3b, v13
	v_exp_f32_e32 v9, v9
	v_lshlrev_b32_e32 v54, 16, v184
	v_mul_f32_e32 v17, 0xbfb8aa3b, v54
	v_exp_f32_e32 v17, v17
	v_add_f32_e32 v9, 1.0, v9
	v_rcp_f32_e32 v43, v9
	v_and_b32_e32 v55, 0xffff0000, v184
	v_add_f32_e32 v17, 1.0, v17
	v_pk_mul_f32 v[64:65], v[172:173], v[16:17] op_sel_hi:[1,0]
	v_pk_mul_f32 v[12:13], v[42:43], v[12:13]
	v_rcp_f32_e32 v62, v17
	v_pk_mul_f32 v[10:11], v[12:13], v[10:11]
	s_nop 0
	v_cvt_pk_bf16_f32 v9, v10, v11
	v_lshl_add_u64 v[10:11], v[40:41], 0, s[14:15]
	v_lshl_add_u64 v[42:43], v[10:11], 1, v[52:53]
	global_store_dwordx2 v[42:43], v[8:9], off offset:1568
	ds_read_b128 v[8:11], v19 offset:128
	ds_read_b128 v[12:15], v2 offset:128
	ds_read_b64_tr_b16 v[52:53], v44 offset:59904
	s_waitcnt lgkmcnt(0)
	v_pk_fma_f32 v[8:9], v[8:9], v[64:65], v[12:13]
	v_mul_f32_e32 v12, 0xbfb8aa3b, v55
	v_exp_f32_e32 v12, v12
	v_and_b32_e32 v57, 0xffff0000, v52
	v_lshlrev_b32_e32 v56, 16, v52
	v_pk_fma_f32 v[8:9], v[18:19], v[56:57], v[8:9] op_sel_hi:[0,1,1]
	v_add_f32_e32 v12, 1.0, v12
	v_rcp_f32_e32 v63, v12
	v_pk_mul_f32 v[56:57], v[168:169], v[16:17] op_sel_hi:[1,0]
	v_pk_mul_f32 v[12:13], v[62:63], v[54:55]
	s_nop 0
	v_pk_mul_f32 v[8:9], v[12:13], v[8:9]
	v_lshlrev_b32_e32 v12, 16, v185
	v_cvt_pk_bf16_f32 v8, v8, v9
	v_mul_f32_e32 v9, 0xbfb8aa3b, v12
	v_exp_f32_e32 v9, v9
	v_and_b32_e32 v13, 0xffff0000, v185
	v_and_b32_e32 v55, 0xffff0000, v53
	v_lshlrev_b32_e32 v54, 16, v53
	v_add_f32_e32 v9, 1.0, v9
	v_rcp_f32_e32 v52, v9
	v_mul_f32_e32 v9, 0xbfb8aa3b, v13
	v_exp_f32_e32 v9, v9
	v_pk_fma_f32 v[10:11], v[10:11], v[56:57], v[14:15]
	v_pk_mul_f32 v[62:63], v[174:175], v[16:17] op_sel_hi:[1,0]
	v_pk_fma_f32 v[10:11], v[18:19], v[54:55], v[10:11] op_sel_hi:[0,1,1]
	v_add_f32_e32 v9, 1.0, v9
	v_rcp_f32_e32 v53, v9
	v_pk_mul_f32 v[16:17], v[170:171], v[16:17] op_sel_hi:[1,0]
	v_pk_mul_f32 v[12:13], v[52:53], v[12:13]
	s_nop 0
	v_pk_mul_f32 v[10:11], v[12:13], v[10:11]
	v_lshlrev_b32_e32 v52, 16, v0
	v_cvt_pk_bf16_f32 v9, v10, v11
	global_store_dwordx2 v[42:43], v[8:9], off offset:1600
	ds_read_b128 v[8:11], v19 offset:192
	ds_read_b128 v[12:15], v2 offset:192
	ds_read_b64_tr_b16 v[44:45], v44 offset:62208
	v_mul_f32_e32 v2, 0xbfb8aa3b, v52
	v_exp_f32_e32 v2, v2
	v_and_b32_e32 v53, 0xffff0000, v0
	s_waitcnt lgkmcnt(0)
	v_pk_fma_f32 v[8:9], v[8:9], v[62:63], v[12:13]
	v_and_b32_e32 v55, 0xffff0000, v44
	v_add_f32_e32 v2, 1.0, v2
	v_rcp_f32_e32 v56, v2
	v_mul_f32_e32 v2, 0xbfb8aa3b, v53
	v_exp_f32_e32 v2, v2
	v_lshlrev_b32_e32 v54, 16, v44
	v_pk_fma_f32 v[8:9], v[18:19], v[54:55], v[8:9] op_sel_hi:[0,1,1]
	v_pk_fma_f32 v[10:11], v[10:11], v[16:17], v[14:15]
	v_add_f32_e32 v2, 1.0, v2
	v_rcp_f32_e32 v57, v2
	s_nop 0
	v_pk_mul_f32 v[12:13], v[56:57], v[52:53]
	s_nop 0
	v_pk_mul_f32 v[8:9], v[12:13], v[8:9]
	v_lshlrev_b32_e32 v12, 16, v1
	v_mul_f32_e32 v2, 0xbfb8aa3b, v12
	v_exp_f32_e32 v2, v2
	v_and_b32_e32 v13, 0xffff0000, v1
	v_and_b32_e32 v53, 0xffff0000, v45
	v_lshlrev_b32_e32 v52, 16, v45
	v_add_f32_e32 v2, 1.0, v2
	v_rcp_f32_e32 v44, v2
	v_mul_f32_e32 v2, 0xbfb8aa3b, v13
	v_exp_f32_e32 v2, v2
	v_pk_fma_f32 v[10:11], v[18:19], v[52:53], v[10:11] op_sel_hi:[0,1,1]
	v_cvt_pk_bf16_f32 v8, v8, v9
	v_add_f32_e32 v2, 1.0, v2
	v_rcp_f32_e32 v45, v2
	s_nop 0
	v_pk_mul_f32 v[12:13], v[44:45], v[12:13]
	s_nop 0
	v_pk_mul_f32 v[10:11], v[12:13], v[10:11]
	s_nop 0
	v_cvt_pk_bf16_f32 v9, v10, v11
	global_store_dwordx2 v[42:43], v[8:9], off offset:1632

.LBB0_567:
	s_and_b64 vcc, exec, s[10:11]
	s_cbranch_vccz .LBB0_563
	v_mov_b32_e32 v2, v161
	v_readlane_b32 s10, v252, 45
	v_and_b32_e32 v40, 15, v2
	v_and_b32_e32 v2, -16, v2
	v_or_b32_e32 v12, s0, v40
	v_mul_u32_u24_e32 v12, 0x48, v12
	v_add_u32_e32 v13, 0, v2
	v_mul_u32_u24_e32 v41, 0x48, v40
	v_add_u32_e32 v8, s10, v2
	v_lshl_add_u32 v12, v12, 1, v13
	v_lshl_add_u32 v41, v41, 1, v13
	ds_read_b128 v[24:27], v12 offset:36864
	ds_read_b128 v[52:55], v12 offset:46080
	ds_read_b128 v[68:71], v41
	ds_read_b128 v[76:79], v41 offset:2304
	ds_read_b128 v[86:89], v41 offset:4608
	ds_read_b128 v[148:151], v41 offset:6912
	ds_read_b128 v[152:155], v41 offset:55296
	ds_read_b128 v[168:171], v41 offset:57600
	ds_read_b128 v[172:175], v41 offset:59904
	ds_read_b128 v[56:59], v41 offset:62208
	ds_read_b128 v[20:23], v12 offset:36928
	ds_read_b128 v[42:45], v12 offset:46144
	ds_read_b128 v[8:11], v8
	s_andn2_b64 vcc, exec, s[40:41]
	s_waitcnt lgkmcnt(10)
	v_mfma_f32_16x16x32_bf16 v[12:15], v[24:27], v[68:71], v[124:127]
	ds_read_b128 v[68:71], v41 offset:64
	s_waitcnt lgkmcnt(10)
	v_mfma_f32_16x16x32_bf16 v[16:19], v[24:27], v[76:79], v[128:131]
	ds_read_b128 v[76:79], v41 offset:2368
	s_waitcnt lgkmcnt(10)
	v_mfma_f32_16x16x32_bf16 v[32:35], v[24:27], v[86:89], v[132:135]
	ds_read_b128 v[86:89], v41 offset:4672
	s_waitcnt lgkmcnt(10)
	v_mfma_f32_16x16x32_bf16 v[36:39], v[24:27], v[148:151], v[136:139]
	ds_read_b128 v[148:151], v41 offset:6976
	s_waitcnt lgkmcnt(10)
	v_mfma_f32_16x16x32_bf16 v[12:15], v[52:55], v[152:155], v[12:15]
	ds_read_b128 v[152:155], v41 offset:55360
	s_waitcnt lgkmcnt(10)
	v_mfma_f32_16x16x32_bf16 v[16:19], v[52:55], v[168:171], v[16:19]
	ds_read_b128 v[168:171], v41 offset:57664
	s_waitcnt lgkmcnt(10)
	v_mfma_f32_16x16x32_bf16 v[32:35], v[52:55], v[172:175], v[32:35]
	ds_read_b128 v[172:175], v41 offset:59968
	s_waitcnt lgkmcnt(10)
	v_mfma_f32_16x16x32_bf16 v[36:39], v[52:55], v[56:59], v[36:39]
	ds_read_b128 v[56:59], v41 offset:62272
	s_waitcnt lgkmcnt(7)
	v_mfma_f32_16x16x32_bf16 v[12:15], v[20:23], v[68:71], v[12:15]
	s_waitcnt lgkmcnt(6)
	v_mfma_f32_16x16x32_bf16 v[16:19], v[20:23], v[76:79], v[16:19]
	s_waitcnt lgkmcnt(5)
	v_mfma_f32_16x16x32_bf16 v[32:35], v[20:23], v[86:89], v[32:35]
	s_waitcnt lgkmcnt(4)
	v_mfma_f32_16x16x32_bf16 v[36:39], v[20:23], v[148:151], v[36:39]
	s_waitcnt lgkmcnt(3)
	v_mfma_f32_16x16x32_bf16 v[12:15], v[42:45], v[152:155], v[12:15]
	s_waitcnt lgkmcnt(2)
	v_mfma_f32_16x16x32_bf16 v[16:19], v[42:45], v[168:171], v[16:19]
	s_waitcnt lgkmcnt(1)
	v_mfma_f32_16x16x32_bf16 v[32:35], v[42:45], v[172:175], v[32:35]
	s_waitcnt lgkmcnt(0)
	v_mfma_f32_16x16x32_bf16 v[36:39], v[42:45], v[56:59], v[36:39]
	s_nop 7
	s_cbranch_vccnz .LBB0_570
	v_mul_u32_u24_e32 v4, 0x90, v40
	v_readlane_b32 s10, v253, 4
	s_nop 1
	v_add3_u32 v2, s10, v2, v4
	ds_read_b128 v[4:7], v2
	ds_read_b128 v[40:43], v2 offset:64
	s_waitcnt lgkmcnt(0)
	v_mfma_f32_16x16x32_bf16 v[4:7], v[24:27], v[4:7], v[92:95]
	ds_read_b128 v[28:31], v2 offset:2304
	ds_read_b128 v[48:51], v2 offset:6912
	ds_read_b128 v[44:47], v2 offset:4672
	v_mfma_f32_16x16x32_bf16 v[4:7], v[20:23], v[40:43], v[4:7]
	ds_read_b128 v[40:43], v2 offset:2368
	s_waitcnt lgkmcnt(0)
	v_mfma_f32_16x16x32_bf16 v[28:31], v[24:27], v[28:31], v[96:99]
	v_mfma_f32_16x16x32_bf16 v[28:31], v[20:23], v[40:43], v[28:31]
	ds_read_b128 v[40:43], v2 offset:4608
	s_nop 2
	v_pk_mul_f32 v[6:7], v[10:11], v[6:7]
	v_pk_mul_f32 v[4:5], v[8:9], v[4:5]
	s_waitcnt lgkmcnt(0)
	v_mfma_f32_16x16x32_bf16 v[40:43], v[24:27], v[40:43], v[100:103]
	v_mul_f32_e64 v82, v10, v30
	v_mul_f32_e64 v83, v11, v31
	v_mfma_f32_16x16x32_bf16 v[40:43], v[20:23], v[44:47], v[40:43]
	ds_read_b128 v[44:47], v2 offset:6976
	v_pk_mul_f32 v[80:81], v[8:9], v[28:29]
	v_mfma_f32_16x16x32_bf16 v[24:27], v[24:27], v[48:51], v[104:107]
	s_waitcnt lgkmcnt(0)
	v_mfma_f32_16x16x32_bf16 v[20:23], v[20:23], v[44:47], v[24:27]
	s_nop 2
	v_mul_f32_e64 v30, v10, v42
	v_mul_f32_e64 v31, v11, v43
	v_pk_mul_f32 v[28:29], v[8:9], v[40:41]
	s_nop 1
	v_pk_mul_f32 v[50:51], v[10:11], v[22:23]
	v_pk_mul_f32 v[48:49], v[8:9], v[20:21]

.LBB0_622:
	s_lshr_b32 s42, s42, 1
	s_cmp_lg_u32 s61, 0
	s_cselect_b64 s[46:47], -1, 0
	s_cmp_eq_u32 s61, 0
	s_cselect_b64 s[38:39], -1, 0
	s_and_b64 s[36:37], s[38:39], exec
	s_cselect_b32 s56, 16, 32
	s_lshl_b32 s57, s61, 4
	v_mov_b32_e32 v111, 0
	s_cmp_ge_u32 s57, s56
	v_mov_b32_e32 v110, v111
	v_mov_b32_e32 v109, v111
	v_mov_b32_e32 v108, v111
	v_mov_b32_e32 v119, v111
	v_mov_b32_e32 v118, v111
	v_mov_b32_e32 v117, v111
	v_mov_b32_e32 v116, v111
	v_mov_b32_e32 v123, v111
	v_mov_b32_e32 v122, v111
	v_mov_b32_e32 v121, v111
	v_mov_b32_e32 v120, v111
	v_mov_b32_e32 v115, v111
	v_mov_b32_e32 v114, v111
	v_mov_b32_e32 v113, v111
	v_mov_b32_e32 v112, v111
	s_cbranch_scc1 .LBB0_745
	global_load_ushort v201, v[50:51], off
	global_load_ushort v200, v[48:49], off
	global_load_ushort v199, v[46:47], off
	global_load_ushort v198, v[44:45], off
	global_load_ushort v197, v[42:43], off
	global_load_ushort v196, v[40:41], off
	global_load_ushort v195, v[38:39], off
	global_load_ushort v194, v[36:37], off
	global_load_ushort v193, v[34:35], off
	global_load_ushort v192, v[32:33], off
	global_load_ushort v191, v[30:31], off
	global_load_ushort v190, v[28:29], off
	global_load_ushort v189, v[8:9], off
	global_load_ushort v188, v[6:7], off
	global_load_ushort v187, v[4:5], off
	global_load_ushort v186, v[0:1], off
	v_writelane_b32 v253, s38, 59
	v_cndmask_b32_e64 v20, 0, 1.0, s[2:3]
	s_mov_b32 s2, s42
	v_writelane_b32 v253, s39, 60
	v_writelane_b32 v253, s66, 61
	v_cndmask_b32_e64 v21, 0, 1.0, s[4:5]
	s_mov_b32 s49, s93
	v_writelane_b32 v253, s67, 62
	v_writelane_b32 v253, s2, 63
	v_cndmask_b32_e64 v25, 0, 1.0, s[12:13]
	v_readlane_b32 s4, v253, 52
	v_cndmask_b32_e64 v26, 0, 1.0, s[14:15]
	v_cndmask_b32_e64 v11, 0, 1.0, s[16:17]
	v_cndmask_b32_e64 v12, 0, 1.0, s[18:19]
	v_cndmask_b32_e64 v13, 0, 1.0, s[20:21]
	v_cndmask_b32_e64 v14, 0, 1.0, s[22:23]
	v_cndmask_b32_e64 v15, 0, 1.0, s[24:25]
	v_cndmask_b32_e64 v16, 0, 1.0, s[26:27]
	s_mov_b32 s43, s93
	v_readlane_b32 s5, v253, 53
	v_readlane_b32 s12, v253, 23
	s_lshr_b32 s39, s58, 6
	v_cndmask_b32_e64 v23, 0, 1.0, s[8:9]
	v_writelane_b32 v252, s3, 0
	s_lshl_b64 s[8:9], s[42:43], 18
	s_lshl_b64 s[2:3], s[48:49], 11
	s_lshl_b64 s[4:5], s[4:5], 2
	v_readlane_b32 s18, v253, 29
	v_readlane_b32 s19, v253, 30
	s_add_u32 s4, s18, s4
	v_cndmask_b32_e64 v22, 0, 1.0, s[6:7]
	v_readlane_b32 s22, v253, 33
	s_addc_u32 s5, s19, s5
	s_lshl_b32 s6, s53, 2
	v_readlane_b32 s23, v253, 34
	s_add_u32 s22, s4, s6
	s_addc_u32 s23, s5, 0
	v_readlane_b32 s4, v253, 48
	s_add_u32 s4, s4, s2
	v_readlane_b32 s2, v253, 50
	s_addc_u32 s5, s2, s3
	v_readlane_b32 s13, v253, 24
	v_readlane_b32 s14, v253, 25
	v_readlane_b32 s15, v253, 26
	v_readlane_b32 s16, v253, 27
	v_readlane_b32 s17, v253, 28
	v_readlane_b32 s20, v253, 31
	v_readlane_b32 s21, v253, 32
	v_readlane_b32 s24, v253, 35
	v_readlane_b32 s25, v253, 36
	v_readlane_b32 s26, v253, 37
	v_readlane_b32 s27, v253, 38
	v_writelane_b32 v253, s4, 48
	v_cndmask_b32_e64 v17, 0, 1.0, s[28:29]
	v_cndmask_b32_e64 v18, 0, 1.0, s[30:31]
	v_writelane_b32 v253, s5, 49
	v_cndmask_b32_e64 v24, 0, 1.0, s[10:11]
	v_readlane_b32 s2, v253, 21
	v_readlane_b32 s3, v253, 22
	s_lshl_b64 s[2:3], s[2:3], 2
	s_add_u32 s2, s24, s2
	s_addc_u32 s3, s25, s3
	v_writelane_b32 v253, s2, 50
	v_cndmask_b32_e64 v19, 0, 1.0, s[34:35]
	s_mul_i32 s38, s77, 0x900
	v_writelane_b32 v253, s3, 51
	s_lshl_b32 s2, s77, 5
	s_add_i32 s37, s2, 0
	s_lshl_b32 s2, s39, 5
	s_add_i32 s66, s2, 0
	s_cmp_eq_u32 s77, 0
	s_cselect_b64 s[28:29], -1, 0
	s_cmp_lg_u32 s77, 0
	s_cselect_b64 s[30:31], -1, 0
	s_lshl_b32 s67, s55, 1
	s_add_i32 s76, s67, 0
	s_add_i32 s2, s76, 0x13c00
	v_writelane_b32 v252, s2, 1
	s_lshl_b32 s3, s77, 10
	v_writelane_b32 v252, s3, 3
	s_add_i32 s81, s3, 0
	s_lshl_b32 s3, s77, 9
	s_add_i32 s3, s3, 0
	s_add_i32 s3, s3, 0x13000
	s_lshl_b32 s2, s55, 2
	v_writelane_b32 v252, s3, 5
	v_readlane_b32 s3, v253, 5
	s_add_i32 s43, s2, 0
	s_add_i32 s83, s3, s2
	s_lshl_b32 s2, s77, 6
	s_add_i32 s78, s43, 0x13800
	s_add_i32 s79, s43, 0x13a00
	s_add_i32 s81, s81, 0x12000
	s_add_i32 s42, s3, s2
	s_cmp_eq_u32 s77, 1
	s_cselect_b64 s[2:3], -1, 0
	s_cmp_eq_u32 s77, 2
	s_cselect_b64 s[4:5], -1, 0
	s_cmp_eq_u32 s77, 3
	s_cselect_b64 s[6:7], -1, 0
	s_cmp_gt_u32 s77, 1
	s_cselect_b64 s[34:35], -1, 0
	s_add_i32 s43, s43, 0x13b00
	s_and_b32 s10, s58, 0xffffff00
	s_cmpk_eq_i32 s10, 0x100
	s_cselect_b64 s[48:49], -1, 0
	s_cmp_lg_u32 s77, 2
	s_mulk_i32 s77, 0x8e0
	s_cselect_b64 s[58:59], -1, 0
	s_add_i32 s36, s76, s77
	s_lshl_b32 s10, s61, 18
	s_add_u32 s77, s8, s10
	s_addc_u32 s82, s9, 0
	s_add_i32 s8, s54, s55
	s_mulk_i32 s8, 0x2200
	s_add_u32 s80, s60, s8
	s_waitcnt vmcnt(17)
	v_mul_f32_e32 v0, 0x3fb8aa3b, v10
	s_addc_u32 s24, s0, 0
	s_add_i32 s9, s8, 0x88000
	v_exp_f32_e32 v183, v0
	s_add_u32 s25, s60, s9
	s_addc_u32 s26, s0, 0
	s_add_i32 s8, s8, 0x66000
	s_add_u32 s27, s60, s8
	v_mov_b32_e32 v112, 0
	s_mulk_i32 s39, 0x900
	s_addc_u32 s0, s0, 0
	v_mov_b32_e32 v113, v112
	v_mov_b32_e32 v114, v112
	v_mov_b32_e32 v115, v112
	v_mov_b32_e32 v120, v112
	v_mov_b32_e32 v121, v112
	v_mov_b32_e32 v122, v112
	v_mov_b32_e32 v123, v112
	v_mov_b32_e32 v116, v112
	v_mov_b32_e32 v117, v112
	v_mov_b32_e32 v118, v112
	v_mov_b32_e32 v119, v112
	v_mov_b32_e32 v108, v112
	v_mov_b32_e32 v109, v112
	v_mov_b32_e32 v110, v112
	v_mov_b32_e32 v111, v112
	s_waitcnt vmcnt(0)
	v_lshlrev_b32_e32 v36, 2, v168
	v_add_u32_e32 v37, 0x1000, v36
	v_add_u32_e32 v38, 0x2000, v36
	global_load_dword v40, v36, s[22:23]
	global_load_dword v41, v36, s[22:23] offset:3072
	global_load_dword v42, v37, s[22:23] offset:2048
	global_load_dword v43, v38, s[22:23] offset:1024
	global_load_dword v44, v36, s[22:23] offset:1024
	global_load_dword v45, v37, s[22:23]
	global_load_dword v46, v37, s[22:23] offset:3072
	global_load_dword v47, v38, s[22:23] offset:2048
	global_load_dword v48, v36, s[22:23] offset:2048
	global_load_dword v49, v37, s[22:23] offset:1024
	global_load_dword v50, v38, s[22:23]
	global_load_dword v51, v38, s[22:23] offset:3072
	v_add_u32_e32 v36, 0x1d000, v36
	s_waitcnt vmcnt(0)
	ds_write_b32 v36, v40
	ds_write_b32 v36, v41 offset:256
	ds_write_b32 v36, v42 offset:512
	ds_write_b32 v36, v43 offset:768
	ds_write_b32 v36, v44 offset:1024
	ds_write_b32 v36, v45 offset:1280
	ds_write_b32 v36, v46 offset:1536
	ds_write_b32 v36, v47 offset:1792
	ds_write_b32 v36, v48 offset:2048
	ds_write_b32 v36, v49 offset:2304
	ds_write_b32 v36, v50 offset:2560
	ds_write_b32 v36, v51 offset:2816
	s_waitcnt lgkmcnt(0)
.LBB0_624:
	v_mov_b32_e32 v0, v168
	v_cndmask_b32_e64 v1, 0, 1, s[44:45]
	v_and_b32_e32 v10, 2, v0
	v_and_b32_e32 v9, 1, v0
	s_mov_b64 s[14:15], -1
	v_cmp_ne_u32_e64 s[8:9], 1, v1
	s_andn2_b64 vcc, exec, s[44:45]
	v_ashrrev_i32_e32 v1, 31, v0
	s_waitcnt vmcnt(20)
	v_lshlrev_b32_e32 v93, 16, v170
	s_waitcnt vmcnt(19)
	v_lshlrev_b32_e32 v92, 16, v171
	s_waitcnt vmcnt(18)
	v_lshlrev_b32_e32 v91, 16, v172
	s_waitcnt vmcnt(0)
	v_lshlrev_b32_e32 v90, 16, v186
	v_lshlrev_b32_e32 v89, 16, v187
	v_lshlrev_b32_e32 v88, 16, v188
	v_lshlrev_b32_e32 v87, 16, v189
	v_lshlrev_b32_e32 v86, 16, v190
	v_lshlrev_b32_e32 v85, 16, v191
	v_lshlrev_b32_e32 v84, 16, v192
	v_lshlrev_b32_e32 v83, 16, v193
	v_lshlrev_b32_e32 v82, 16, v194
	v_lshlrev_b32_e32 v81, 16, v195
	v_lshlrev_b32_e32 v80, 16, v196
	v_lshlrev_b32_e32 v79, 16, v197
	v_lshlrev_b32_e32 v76, 16, v198
	v_lshlrev_b32_e32 v78, 16, v199
	v_lshlrev_b32_e32 v77, 16, v200
	v_lshlrev_b32_e32 v27, 16, v201
	v_cmp_eq_u32_e64 s[12:13], 0, v10
	v_cmp_eq_u32_e64 s[10:11], 0, v9
	s_cbranch_vccnz .LBB0_626
	v_lshlrev_b32_e32 v4, 2, v0
	v_add_u32_e32 v4, 0x1d000, v4
	s_mov_b64 s[14:15], 0
	ds_read_b32 v33, v4
	ds_read_b32 v34, v4 offset:256
	ds_read_b32 v35, v4 offset:512
	ds_read_b32 v36, v4 offset:768
	s_waitcnt lgkmcnt(0)
	v_mul_f32_e32 v2, v34, v92
	v_fmac_f32_e32 v2, v33, v93
	v_fmac_f32_e32 v2, v35, v91
	v_fmac_f32_e32 v2, v36, v90
	v_mul_f32_e32 v6, 0xbfb8aa3b, v2
	v_exp_f32_e32 v6, v6
	s_nop 0
	v_add_f32_e32 v6, 1.0, v6
	v_rcp_f32_e32 v6, v6
	s_nop 0
	v_mul_f32_e32 v2, v2, v6
	v_mul_f32_e32 v6, v34, v91
	v_fmac_f32_e32 v6, v33, v92
	v_fmac_f32_e32 v6, v35, v90
	v_fmac_f32_e32 v6, v36, v89
	v_mul_f32_e32 v7, 0xbfb8aa3b, v6
	v_exp_f32_e32 v7, v7
	s_nop 0
	v_add_f32_e32 v7, 1.0, v7
	v_rcp_f32_e32 v7, v7
	s_nop 0
	v_mul_f32_e32 v6, v6, v7
	v_mul_f32_e32 v7, v34, v90
	v_fmac_f32_e32 v7, v33, v91
	v_fmac_f32_e32 v7, v35, v89
	v_fmac_f32_e32 v7, v36, v88
	v_mul_f32_e32 v8, 0xbfb8aa3b, v7
	v_exp_f32_e32 v8, v8
	s_nop 0
	v_add_f32_e32 v8, 1.0, v8
	v_rcp_f32_e32 v8, v8
	s_nop 0
	v_mul_f32_e32 v7, v7, v8
	v_mul_f32_e32 v8, v34, v89
	v_fmac_f32_e32 v8, v33, v90
	v_fmac_f32_e32 v8, v35, v88
	v_fmac_f32_e32 v8, v36, v87
	v_mul_f32_e32 v28, 0xbfb8aa3b, v8
	v_exp_f32_e32 v28, v28
	s_nop 0
	v_add_f32_e32 v28, 1.0, v28
	v_rcp_f32_e32 v28, v28
	s_nop 0
	v_mul_f32_e32 v8, v8, v28
	v_mul_f32_e32 v28, v34, v88
	v_fmac_f32_e32 v28, v33, v89
	v_fmac_f32_e32 v28, v35, v87
	v_fmac_f32_e32 v28, v36, v86
	v_mul_f32_e32 v29, 0xbfb8aa3b, v28
	v_exp_f32_e32 v29, v29
	s_nop 0
	v_add_f32_e32 v29, 1.0, v29
	v_rcp_f32_e32 v29, v29
	s_nop 0
	v_mul_f32_e32 v28, v28, v29
	v_mul_f32_e32 v29, v34, v87
	v_fmac_f32_e32 v29, v33, v88
	v_fmac_f32_e32 v29, v35, v86
	v_fmac_f32_e32 v29, v36, v85
	v_mul_f32_e32 v30, 0xbfb8aa3b, v29
	v_exp_f32_e32 v30, v30
	v_mul_f32_e32 v44, v28, v28
	v_add_f32_e32 v30, 1.0, v30
	v_rcp_f32_e32 v30, v30
	s_nop 0
	v_mul_f32_e32 v29, v29, v30
	v_mul_f32_e32 v30, v34, v86
	v_fmac_f32_e32 v30, v33, v87
	v_fmac_f32_e32 v30, v35, v85
	v_fmac_f32_e32 v30, v36, v84
	v_mul_f32_e32 v31, 0xbfb8aa3b, v30
	v_exp_f32_e32 v31, v31
	v_mul_f32_e32 v45, v29, v29
	v_add_f32_e32 v31, 1.0, v31
	v_rcp_f32_e32 v31, v31
	s_nop 0
	v_mul_f32_e32 v30, v30, v31
	v_mul_f32_e32 v31, v34, v85
	v_fmac_f32_e32 v31, v33, v86
	v_fmac_f32_e32 v31, v35, v84
	v_fmac_f32_e32 v31, v36, v83
	v_mul_f32_e32 v32, 0xbfb8aa3b, v31
	v_exp_f32_e32 v32, v32
	v_mul_f32_e32 v46, v30, v30
	v_add_f32_e32 v32, 1.0, v32
	v_rcp_f32_e32 v32, v32
	s_nop 0
	v_mul_f32_e32 v31, v31, v32
	v_mul_f32_e32 v32, v34, v84
	v_fmac_f32_e32 v32, v33, v85
	v_fmac_f32_e32 v32, v35, v83
	v_fmac_f32_e32 v32, v36, v82
	v_mul_f32_e32 v37, 0xbfb8aa3b, v32
	v_exp_f32_e32 v37, v37
	v_mul_f32_e32 v47, v31, v31
	v_add_f32_e32 v37, 1.0, v37
	v_rcp_f32_e32 v37, v37
	s_nop 0
	v_mul_f32_e32 v32, v32, v37
	v_mul_f32_e32 v37, v34, v83
	v_fmac_f32_e32 v37, v33, v84
	v_fmac_f32_e32 v37, v35, v82
	v_fmac_f32_e32 v37, v36, v81
	v_mul_f32_e32 v38, 0xbfb8aa3b, v37
	v_exp_f32_e32 v38, v38
	v_mul_f32_e32 v48, v32, v32
	v_add_f32_e32 v38, 1.0, v38
	v_rcp_f32_e32 v38, v38
	s_nop 0
	v_mul_f32_e32 v42, v37, v38
	v_mul_f32_e32 v37, v34, v82
	v_fmac_f32_e32 v37, v33, v83
	v_fmac_f32_e32 v37, v35, v81
	v_fmac_f32_e32 v37, v36, v80
	v_mul_f32_e32 v38, 0xbfb8aa3b, v37
	v_exp_f32_e32 v38, v38
	v_mul_f32_e32 v49, v42, v42
	v_add_f32_e32 v38, 1.0, v38
	v_rcp_f32_e32 v38, v38
	s_nop 0
	v_mul_f32_e32 v41, v37, v38
	v_mul_f32_e32 v37, v34, v81
	v_fmac_f32_e32 v37, v33, v82
	v_fmac_f32_e32 v37, v35, v80
	v_fmac_f32_e32 v37, v36, v79
	v_mul_f32_e32 v38, 0xbfb8aa3b, v37
	v_exp_f32_e32 v38, v38
	v_mul_f32_e32 v50, v41, v41
	v_add_f32_e32 v38, 1.0, v38
	v_rcp_f32_e32 v38, v38
	s_nop 0
	v_mul_f32_e32 v40, v37, v38
	v_mul_f32_e32 v37, v34, v80
	v_fmac_f32_e32 v37, v33, v81
	v_fmac_f32_e32 v37, v35, v79
	v_fmac_f32_e32 v37, v36, v76
	v_mul_f32_e32 v38, 0xbfb8aa3b, v37
	v_exp_f32_e32 v38, v38
	v_mul_f32_e32 v51, v40, v40
	v_add_f32_e32 v38, 1.0, v38
	v_rcp_f32_e32 v38, v38
	s_nop 0
	v_mul_f32_e32 v39, v37, v38
	v_mul_f32_e32 v37, v34, v79
	v_fmac_f32_e32 v37, v33, v80
	v_fmac_f32_e32 v37, v35, v76
	v_fmac_f32_e32 v37, v36, v78
	v_mul_f32_e32 v38, 0xbfb8aa3b, v37
	v_exp_f32_e32 v38, v38
	v_mul_f32_e32 v52, v39, v39
	v_add_f32_e32 v38, 1.0, v38
	v_rcp_f32_e32 v38, v38
	s_nop 0
	v_mul_f32_e32 v38, v37, v38
	v_mul_f32_e32 v37, v34, v76
	v_mul_f32_e32 v34, v34, v78
	v_fmac_f32_e32 v37, v33, v79
	v_fmac_f32_e32 v34, v33, v76
	v_fmac_f32_e32 v37, v35, v78
	v_fmac_f32_e32 v34, v35, v77
	v_fmac_f32_e32 v37, v36, v77
	v_fmac_f32_e32 v34, v36, v27
	v_mul_f32_e32 v43, 0xbfb8aa3b, v37
	v_mul_f32_e32 v33, 0xbfb8aa3b, v34
	v_exp_f32_e32 v43, v43
	v_exp_f32_e32 v33, v33
	v_mul_f32_e32 v35, v6, v6
	v_mul_f32_e32 v36, v7, v7
	v_add_f32_e32 v43, 1.0, v43
	v_add_f32_e32 v33, 1.0, v33
	v_rcp_f32_e32 v43, v43
	v_rcp_f32_e32 v33, v33
	v_mul_f32_e32 v53, v38, v38
	v_mul_f32_e32 v37, v37, v43
	v_mul_f32_e32 v33, v34, v33
	v_mul_f32_e32 v34, v2, v2
	v_mul_f32_e32 v43, v8, v8
	v_mul_f32_e32 v54, v37, v37
	v_mul_f32_e32 v55, v33, v33
	s_nop 1
	v_permlane32_swap_b32 v34, v48
	s_nop 1
	v_permlane32_swap_b32 v35, v49
	s_nop 1
	v_permlane32_swap_b32 v36, v50
	s_nop 1
	v_permlane32_swap_b32 v43, v51
	s_nop 1
	v_permlane32_swap_b32 v44, v52
	s_nop 1
	v_permlane32_swap_b32 v45, v53
	s_nop 1
	v_permlane32_swap_b32 v46, v54
	s_nop 1
	v_permlane32_swap_b32 v47, v55
	s_nop 0
	v_add_f32_e32 v34, v34, v48
	v_add_f32_e32 v35, v35, v49
	v_add_f32_e32 v36, v36, v50
	v_add_f32_e32 v43, v43, v51
	v_add_f32_e32 v44, v44, v52
	v_add_f32_e32 v45, v45, v53
	v_add_f32_e32 v46, v46, v54
	v_add_f32_e32 v47, v47, v55
	s_nop 1
	v_permlane16_swap_b32 v34, v44
	s_nop 1
	v_permlane16_swap_b32 v35, v45
	s_nop 1
	v_permlane16_swap_b32 v36, v46
	s_nop 1
	v_permlane16_swap_b32 v43, v47
	s_nop 0
	v_add_f32_e32 v34, v34, v44
	v_add_f32_e32 v35, v35, v45
	v_add_f32_e32 v36, v36, v46
	v_add_f32_e32 v43, v43, v47
	v_cndmask_b32_e64 v44, v34, v36, s[12:13]
	v_cndmask_b32_e64 v34, v36, v34, s[12:13]
	v_cndmask_b32_e64 v36, v35, v43, s[12:13]
	v_cndmask_b32_e64 v35, v43, v35, s[12:13]
	v_add_f32_dpp v34, v44, v34 quad_perm:[2,3,0,1] row_mask:0xf bank_mask:0xf bound_ctrl:1
	v_and_b32_e32 v45, 0xffff0000, v181
	v_add_f32_dpp v35, v36, v35 quad_perm:[2,3,0,1] row_mask:0xf bank_mask:0xf bound_ctrl:1
	v_cndmask_b32_e64 v36, v34, v35, s[10:11]
	v_cndmask_b32_e64 v34, v35, v34, s[10:11]
	v_lshlrev_b32_e32 v44, 16, v181
	v_and_b32_e32 v43, 0xffff0000, v180
	v_add_f32_dpp v34, v36, v34 quad_perm:[1,0,3,2] row_mask:0xf bank_mask:0xf bound_ctrl:1
	s_nop 1
	v_add_f32_dpp v34, v34, v34 row_ror:4 row_mask:0xf bank_mask:0xf bound_ctrl:1
	s_nop 1
	v_add_f32_dpp v34, v34, v34 row_ror:8 row_mask:0xf bank_mask:0xf bound_ctrl:1
	s_nop 0
	v_readlane_b32 s10, v34, 0
	s_nop 1
	v_add_f32_e32 v35, s10, v158
	v_cmp_gt_f32_e32 vcc, s75, v35
	v_mul_f32_e32 v36, 0x4b800000, v35
	v_readlane_b32 s10, v34, 1
	v_cndmask_b32_e32 v35, v35, v36, vcc
	v_rsq_f32_e32 v35, v35
	s_nop 0
	v_mul_f32_e32 v36, 0x45800000, v35
	v_cndmask_b32_e32 v35, v35, v36, vcc
	v_mul_f32_e32 v2, v2, v35
	v_mul_f32_e32 v2, 0x3e000000, v2
	v_cvt_pk_bf16_f32 v35, v2, s0
	v_lshl_add_u32 v2, v0, 1, s36
	ds_write_b16 v2, v35
	v_add_f32_e32 v35, s10, v158
	v_cmp_gt_f32_e32 vcc, s75, v35
	v_mul_f32_e32 v36, 0x4b800000, v35
	v_readlane_b32 s10, v34, 2
	v_cndmask_b32_e32 v35, v35, v36, vcc
	v_rsq_f32_e32 v35, v35
	s_nop 0
	v_mul_f32_e32 v36, 0x45800000, v35
	v_cndmask_b32_e32 v35, v35, v36, vcc
	v_mul_f32_e32 v6, v6, v35
	v_mul_f32_e32 v6, 0x3e000000, v6
	v_cvt_pk_bf16_f32 v6, v6, s0
	ds_write_b16 v2, v6 offset:144
	v_add_f32_e32 v6, s10, v158
	v_cmp_gt_f32_e32 vcc, s75, v6
	v_mul_f32_e32 v35, 0x4b800000, v6
	v_readlane_b32 s10, v34, 3
	v_cndmask_b32_e32 v6, v6, v35, vcc
	v_rsq_f32_e32 v6, v6
	v_lshlrev_b32_e32 v36, 16, v176
	v_mul_f32_e32 v35, 0x45800000, v6
	v_cndmask_b32_e32 v6, v6, v35, vcc
	v_mul_f32_e32 v6, v7, v6
	v_mul_f32_e32 v6, 0x3e000000, v6
	v_cvt_pk_bf16_f32 v6, v6, s0
	ds_write_b16 v2, v6 offset:288
	v_add_f32_e32 v6, s10, v158
	v_cmp_gt_f32_e32 vcc, s75, v6
	v_mul_f32_e32 v7, 0x4b800000, v6
	v_readlane_b32 s10, v34, 16
	v_cndmask_b32_e32 v6, v6, v7, vcc
	v_rsq_f32_e32 v6, v6
	v_and_b32_e32 v35, 0xffff0000, v177
	v_mul_f32_e32 v7, 0x45800000, v6
	v_cndmask_b32_e32 v6, v6, v7, vcc
	v_mul_f32_e32 v6, v8, v6
	v_mul_f32_e32 v6, 0x3e000000, v6
	v_cvt_pk_bf16_f32 v6, v6, s0
	ds_write_b16 v2, v6 offset:432
	v_add_f32_e32 v6, s10, v158
	v_cmp_gt_f32_e32 vcc, s75, v6
	v_mul_f32_e32 v7, 0x4b800000, v6
	v_readlane_b32 s10, v34, 17
	v_cndmask_b32_e32 v6, v6, v7, vcc
	v_rsq_f32_e32 v6, v6
	s_nop 0
	v_mul_f32_e32 v7, 0x45800000, v6
	v_cndmask_b32_e32 v6, v6, v7, vcc
	v_mul_f32_e32 v6, v28, v6
	v_mul_f32_e32 v6, 0x3e000000, v6
	v_cvt_pk_bf16_f32 v6, v6, s0
	ds_write_b16 v2, v6 offset:576
	v_add_f32_e32 v6, s10, v158
	v_cmp_gt_f32_e32 vcc, s75, v6
	v_mul_f32_e32 v7, 0x4b800000, v6
	v_readlane_b32 s10, v34, 18
	v_cndmask_b32_e32 v6, v6, v7, vcc
	v_rsq_f32_e32 v6, v6
	v_add_u32_e32 v28, 0xb00, v0
	v_mul_f32_e32 v7, 0x45800000, v6
	v_cndmask_b32_e32 v6, v6, v7, vcc
	v_mul_f32_e32 v6, v29, v6
	v_mul_f32_e32 v6, 0x3e000000, v6
	v_cvt_pk_bf16_f32 v6, v6, s0
	ds_write_b16 v2, v6 offset:720
	v_add_f32_e32 v6, s10, v158
	v_cmp_gt_f32_e32 vcc, s75, v6
	v_mul_f32_e32 v7, 0x4b800000, v6
	v_readlane_b32 s10, v34, 19
	v_cndmask_b32_e32 v6, v6, v7, vcc
	v_rsq_f32_e32 v6, v6
	v_ashrrev_i32_e32 v29, 31, v28
	v_lshl_add_u64 v[28:29], v[28:29], 2, s[22:23]
	v_mul_f32_e32 v7, 0x45800000, v6
	v_cndmask_b32_e32 v6, v6, v7, vcc
	v_mul_f32_e32 v6, v30, v6
	v_mul_f32_e32 v6, 0x3e000000, v6
	v_cvt_pk_bf16_f32 v6, v6, s0
	ds_write_b16 v2, v6 offset:864
	v_add_f32_e32 v6, s10, v158
	v_cmp_gt_f32_e32 vcc, s75, v6
	v_mul_f32_e32 v7, 0x4b800000, v6
	v_readlane_b32 s10, v34, 32
	v_cndmask_b32_e32 v6, v6, v7, vcc
	v_rsq_f32_e32 v6, v6
	v_lshlrev_b32_e32 v30, 16, v173
	v_mul_f32_e32 v7, 0x45800000, v6
	v_cndmask_b32_e32 v6, v6, v7, vcc
	v_mul_f32_e32 v6, v31, v6
	v_mul_f32_e32 v6, 0x3e000000, v6
	v_cvt_pk_bf16_f32 v6, v6, s0
	ds_write_b16 v2, v6 offset:1008
	v_add_f32_e32 v6, s10, v158
	v_cmp_gt_f32_e32 vcc, s75, v6
	v_mul_f32_e32 v7, 0x4b800000, v6
	v_readlane_b32 s10, v34, 33
	v_cndmask_b32_e32 v6, v6, v7, vcc
	v_rsq_f32_e32 v6, v6
	v_and_b32_e32 v31, 0xffff0000, v173
	v_mul_f32_e32 v7, 0x45800000, v6
	v_cndmask_b32_e32 v6, v6, v7, vcc
	v_mul_f32_e32 v6, v32, v6
	v_mul_f32_e32 v6, 0x3e000000, v6
	v_cvt_pk_bf16_f32 v6, v6, s0
	ds_write_b16 v2, v6 offset:1152
	v_add_f32_e32 v6, s10, v158
	v_cmp_gt_f32_e32 vcc, s75, v6
	v_mul_f32_e32 v7, 0x4b800000, v6
	v_readlane_b32 s10, v34, 34
	v_cndmask_b32_e32 v6, v6, v7, vcc
	v_rsq_f32_e32 v6, v6
	v_lshlrev_b32_e32 v32, 16, v182
	v_mul_f32_e32 v7, 0x45800000, v6
	v_cndmask_b32_e32 v6, v6, v7, vcc
	v_mul_f32_e32 v6, v42, v6
	v_mul_f32_e32 v6, 0x3e000000, v6
	v_cvt_pk_bf16_f32 v6, v6, s0
	ds_write_b16 v2, v6 offset:1296
	v_add_f32_e32 v6, s10, v158
	v_cmp_gt_f32_e32 vcc, s75, v6
	v_mul_f32_e32 v7, 0x4b800000, v6
	v_readlane_b32 s10, v34, 35
	v_cndmask_b32_e32 v6, v6, v7, vcc
	v_rsq_f32_e32 v6, v6
	v_lshlrev_b32_e32 v42, 16, v180
	v_mul_f32_e32 v7, 0x45800000, v6
	v_cndmask_b32_e32 v6, v6, v7, vcc
	v_mul_f32_e32 v6, v41, v6
	v_mul_f32_e32 v6, 0x3e000000, v6
	v_cvt_pk_bf16_f32 v6, v6, s0
	ds_write_b16 v2, v6 offset:1440
	v_add_f32_e32 v6, s10, v158
	v_cmp_gt_f32_e32 vcc, s75, v6
	v_mul_f32_e32 v7, 0x4b800000, v6
	v_readlane_b32 s10, v34, 48
	v_cndmask_b32_e32 v6, v6, v7, vcc
	v_rsq_f32_e32 v6, v6
	v_and_b32_e32 v41, 0xffff0000, v179
	v_mul_f32_e32 v7, 0x45800000, v6
	v_cndmask_b32_e32 v6, v6, v7, vcc
	v_mul_f32_e32 v6, v40, v6
	v_mul_f32_e32 v6, 0x3e000000, v6
	v_cvt_pk_bf16_f32 v6, v6, s0
	ds_write_b16 v2, v6 offset:1584
	v_add_f32_e32 v6, s10, v158
	v_cmp_gt_f32_e32 vcc, s75, v6
	v_mul_f32_e32 v7, 0x4b800000, v6
	v_readlane_b32 s10, v34, 49
	v_cndmask_b32_e32 v6, v6, v7, vcc
	v_rsq_f32_e32 v6, v6
	v_lshlrev_b32_e32 v40, 16, v179
	v_mul_f32_e32 v7, 0x45800000, v6
	v_cndmask_b32_e32 v6, v6, v7, vcc
	v_mul_f32_e32 v6, v39, v6
	v_mul_f32_e32 v6, 0x3e000000, v6
	v_cvt_pk_bf16_f32 v6, v6, s0
	ds_write_b16 v2, v6 offset:1728
	v_add_f32_e32 v6, s10, v158
	v_cmp_gt_f32_e32 vcc, s75, v6
	v_mul_f32_e32 v7, 0x4b800000, v6
	v_readlane_b32 s10, v34, 50
	v_cndmask_b32_e32 v6, v6, v7, vcc
	v_rsq_f32_e32 v6, v6
	v_and_b32_e32 v39, 0xffff0000, v178
	v_mul_f32_e32 v7, 0x45800000, v6
	v_cndmask_b32_e32 v6, v6, v7, vcc
	v_mul_f32_e32 v6, v38, v6
	v_mul_f32_e32 v6, 0x3e000000, v6
	v_cvt_pk_bf16_f32 v6, v6, s0
	ds_write_b16 v2, v6 offset:1872
	v_add_f32_e32 v6, s10, v158
	v_cmp_gt_f32_e32 vcc, s75, v6
	v_mul_f32_e32 v7, 0x4b800000, v6
	v_readlane_b32 s10, v34, 51
	v_cndmask_b32_e32 v6, v6, v7, vcc
	v_rsq_f32_e32 v6, v6
	v_lshlrev_b32_e32 v38, 16, v178
	v_lshlrev_b32_e32 v34, 16, v177
	v_mul_f32_e32 v7, 0x45800000, v6
	v_cndmask_b32_e32 v6, v6, v7, vcc
	v_mul_f32_e32 v6, v37, v6
	v_mul_f32_e32 v6, 0x3e000000, v6
	v_cvt_pk_bf16_f32 v6, v6, s0
	ds_write_b16 v2, v6 offset:2016
	v_add_f32_e32 v6, s10, v158
	v_cmp_gt_f32_e32 vcc, s75, v6
	v_mul_f32_e32 v7, 0x4b800000, v6
	v_and_b32_e32 v37, 0xffff0000, v176
	v_cndmask_b32_e32 v6, v6, v7, vcc
	v_rsq_f32_e32 v6, v6
	s_nop 0
	v_mul_f32_e32 v7, 0x45800000, v6
	v_cndmask_b32_e32 v6, v6, v7, vcc
	v_mul_f32_e32 v6, v33, v6
	v_mul_f32_e32 v6, 0x3e000000, v6
	v_cvt_pk_bf16_f32 v6, v6, s0
	ds_write_b16 v2, v6 offset:2160
	ds_read_b32 v2, v4 offset:2304
	v_and_b32_e32 v33, 0xffff0000, v182
	ds_read_b32 v8, v4 offset:2816
	ds_read_b32 v6, v4 offset:2560
	ds_read_b32 v4, v4 offset:2048
	v_pk_mov_b32 v[48:49], v[30:31], v[32:33] op_sel:[1,0]
	v_pk_mov_b32 v[46:47], v[32:33], v[44:45] op_sel:[1,0]
	v_lshlrev_b32_e32 v28, 16, v175
	v_and_b32_e32 v29, 0xffff0000, v175
	s_waitcnt lgkmcnt(0)
	v_pk_mul_f32 v[48:49], v[2:3], v[48:49] op_sel_hi:[0,1]
	v_pk_fma_f32 v[30:31], v[4:5], v[30:31], v[48:49] op_sel_hi:[0,1,1]
	v_pk_fma_f32 v[30:31], v[6:7], v[32:33], v[30:31] op_sel_hi:[0,1,1]
	v_pk_fma_f32 v[30:31], v[8:9], v[46:47], v[30:31] op_sel_hi:[0,1,1]
	v_mul_f32_e32 v5, 0xbfb8aa3b, v30
	v_exp_f32_e32 v5, v5
	v_pk_mul_f32 v[46:47], v[2:3], v[46:47] op_sel_hi:[0,1]
	v_add_f32_e32 v5, 1.0, v5
	v_rcp_f32_e32 v48, v5
	v_mul_f32_e32 v5, 0xbfb8aa3b, v31
	v_exp_f32_e32 v5, v5
	s_nop 0
	v_add_f32_e32 v5, 1.0, v5
	v_rcp_f32_e32 v49, v5
	v_pk_fma_f32 v[32:33], v[4:5], v[32:33], v[46:47] op_sel_hi:[0,1,1]
	v_pk_fma_f32 v[32:33], v[6:7], v[44:45], v[32:33] op_sel_hi:[0,1,1]
	v_pk_mul_f32 v[30:31], v[30:31], v[48:49]
	v_pk_mov_b32 v[48:49], v[44:45], v[42:43] op_sel:[1,0]
	s_nop 0
	v_pk_fma_f32 v[32:33], v[8:9], v[48:49], v[32:33] op_sel_hi:[0,1,1]
	v_mul_f32_e32 v5, 0xbfb8aa3b, v32
	v_exp_f32_e32 v5, v5
	v_pk_mul_f32 v[48:49], v[2:3], v[48:49] op_sel_hi:[0,1]
	v_add_f32_e32 v5, 1.0, v5
	v_rcp_f32_e32 v46, v5
	v_mul_f32_e32 v5, 0xbfb8aa3b, v33
	v_exp_f32_e32 v5, v5
	s_nop 0
	v_add_f32_e32 v5, 1.0, v5
	v_rcp_f32_e32 v47, v5
	v_pk_fma_f32 v[44:45], v[4:5], v[44:45], v[48:49] op_sel_hi:[0,1,1]
	v_pk_fma_f32 v[44:45], v[6:7], v[42:43], v[44:45] op_sel_hi:[0,1,1]
	v_pk_mul_f32 v[32:33], v[32:33], v[46:47]
	v_pk_mov_b32 v[46:47], v[42:43], v[40:41] op_sel:[1,0]
	s_nop 0
	v_pk_fma_f32 v[44:45], v[8:9], v[46:47], v[44:45] op_sel_hi:[0,1,1]
	v_mul_f32_e32 v5, 0xbfb8aa3b, v44
	v_exp_f32_e32 v5, v5
	v_pk_mul_f32 v[46:47], v[2:3], v[46:47] op_sel_hi:[0,1]
	v_add_f32_e32 v5, 1.0, v5
	v_rcp_f32_e32 v48, v5
	v_mul_f32_e32 v5, 0xbfb8aa3b, v45
	v_exp_f32_e32 v5, v5
	s_nop 0
	v_add_f32_e32 v5, 1.0, v5
	v_rcp_f32_e32 v49, v5
	v_pk_fma_f32 v[42:43], v[4:5], v[42:43], v[46:47] op_sel_hi:[0,1,1]
	v_pk_fma_f32 v[42:43], v[6:7], v[40:41], v[42:43] op_sel_hi:[0,1,1]
	v_pk_mul_f32 v[44:45], v[44:45], v[48:49]
	v_pk_mov_b32 v[48:49], v[40:41], v[38:39] op_sel:[1,0]
	s_nop 0
	v_pk_fma_f32 v[42:43], v[8:9], v[48:49], v[42:43] op_sel_hi:[0,1,1]
	v_mul_f32_e32 v5, 0xbfb8aa3b, v42
	v_exp_f32_e32 v5, v5
	v_pk_mul_f32 v[48:49], v[2:3], v[48:49] op_sel_hi:[0,1]
	v_add_f32_e32 v5, 1.0, v5
	v_rcp_f32_e32 v46, v5
	v_mul_f32_e32 v5, 0xbfb8aa3b, v43
	v_exp_f32_e32 v5, v5
	s_nop 0
	v_add_f32_e32 v5, 1.0, v5
	v_rcp_f32_e32 v47, v5
	v_pk_fma_f32 v[40:41], v[4:5], v[40:41], v[48:49] op_sel_hi:[0,1,1]
	v_pk_fma_f32 v[40:41], v[6:7], v[38:39], v[40:41] op_sel_hi:[0,1,1]
	v_pk_mul_f32 v[42:43], v[42:43], v[46:47]
	v_pk_mov_b32 v[46:47], v[38:39], v[36:37] op_sel:[1,0]
	s_nop 0
	v_pk_fma_f32 v[40:41], v[8:9], v[46:47], v[40:41] op_sel_hi:[0,1,1]
	v_mul_f32_e32 v5, 0xbfb8aa3b, v40
	v_exp_f32_e32 v5, v5
	v_pk_mul_f32 v[46:47], v[2:3], v[46:47] op_sel_hi:[0,1]
	v_add_f32_e32 v5, 1.0, v5
	v_rcp_f32_e32 v48, v5
	v_mul_f32_e32 v5, 0xbfb8aa3b, v41
	v_exp_f32_e32 v5, v5
	s_nop 0
	v_add_f32_e32 v5, 1.0, v5
	v_pk_fma_f32 v[38:39], v[4:5], v[38:39], v[46:47] op_sel_hi:[0,1,1]
	v_pk_fma_f32 v[38:39], v[6:7], v[36:37], v[38:39] op_sel_hi:[0,1,1]
	v_mov_b32_e32 v46, v37
	v_mov_b32_e32 v47, v35
	v_pk_fma_f32 v[38:39], v[8:9], v[46:47], v[38:39] op_sel_hi:[0,1,1]
	v_rcp_f32_e32 v49, v5
	v_mul_f32_e32 v5, 0xbfb8aa3b, v38
	v_exp_f32_e32 v5, v5
	v_pk_mul_f32 v[40:41], v[40:41], v[48:49]
	v_mul_f32_e32 v48, v6, v29
	v_add_f32_e32 v5, 1.0, v5
	v_rcp_f32_e32 v46, v5
	v_mul_f32_e32 v5, 0xbfb8aa3b, v39
	v_exp_f32_e32 v5, v5
	s_nop 0
	v_add_f32_e32 v5, 1.0, v5
	v_rcp_f32_e32 v47, v5
	s_nop 0
	v_pk_mul_f32 v[38:39], v[38:39], v[46:47]
	v_pk_mul_f32 v[46:47], v[2:3], v[34:35] op_sel_hi:[0,1]
	v_pk_fma_f32 v[36:37], v[4:5], v[36:37], v[46:47] op_sel_hi:[0,1,1]
	v_mul_f32_e32 v46, v4, v35
	v_pk_mov_b32 v[34:35], v[34:35], v[28:29] op_sel:[1,0]
	s_nop 0
	v_pk_fma_f32 v[34:35], v[6:7], v[34:35], v[36:37] op_sel_hi:[0,1,1]
	v_pk_fma_f32 v[34:35], v[8:9], v[28:29], v[34:35] op_sel_hi:[0,1,1]
	v_mul_f32_e32 v5, 0xbfb8aa3b, v34
	v_exp_f32_e32 v5, v5
	v_mov_b32_e32 v7, v8
	v_add_f32_e32 v5, 1.0, v5
	v_rcp_f32_e32 v36, v5
	v_mul_f32_e32 v5, 0xbfb8aa3b, v35
	v_exp_f32_e32 v5, v5
	s_nop 0
	v_add_f32_e32 v5, 1.0, v5
	v_rcp_f32_e32 v37, v5
	v_mov_b32_e32 v5, v2
	v_pk_mul_f32 v[4:5], v[4:5], v[28:29]
	v_and_b32_e32 v29, 0xffff0000, v174
	v_pk_mul_f32 v[34:35], v[34:35], v[36:37]
	v_mul_f32_e32 v36, v2, v28
	v_lshlrev_b32_e32 v28, 16, v174
	v_pk_mul_f32 v[6:7], v[6:7], v[28:29]
	v_mov_b32_e32 v47, v4
	v_mov_b32_e32 v37, v5
	v_pk_add_f32 v[4:5], v[46:47], v[36:37]
	v_mov_b32_e32 v49, v6
	v_mul_f32_e32 v50, v8, v28
	v_pk_add_f32 v[4:5], v[4:5], v[48:49]
	v_mov_b32_e32 v51, v7
	v_pk_add_f32 v[4:5], v[4:5], v[50:51]
	v_cvt_pk_bf16_f32 v28, v40, v41
	v_mul_f32_e32 v2, 0xbfb8aa3b, v4
	v_exp_f32_e32 v2, v2
	v_cvt_pk_bf16_f32 v29, v38, v39
	v_add_f32_e32 v2, 1.0, v2
	v_rcp_f32_e32 v6, v2
	v_mul_f32_e32 v2, 0xbfb8aa3b, v5
	v_exp_f32_e32 v2, v2
	s_nop 0
	v_add_f32_e32 v2, 1.0, v2
	v_rcp_f32_e32 v7, v2
	v_mul_lo_u32 v2, v0, s89
	v_add_u32_e32 v2, s37, v2
	v_pk_mul_f32 v[36:37], v[4:5], v[6:7]
	v_cvt_pk_bf16_f32 v4, v30, v31
	v_cvt_pk_bf16_f32 v5, v32, v33
	v_cvt_pk_bf16_f32 v6, v44, v45
	v_cvt_pk_bf16_f32 v7, v42, v43
	v_cvt_pk_bf16_f32 v30, v34, v35
	v_cvt_pk_bf16_f32 v31, v36, v37
	ds_write_b128 v2, v[4:7] offset:27648
	ds_write_b128 v2, v[28:31] offset:27664
.LBB0_626:
	v_mov_b64_e32 v[42:43], v[34:35]
	v_mov_b64_e32 v[40:41], v[32:33]
	v_mov_b64_e32 v[38:39], v[30:31]
	v_mov_b64_e32 v[36:37], v[28:29]
	v_mov_b64_e32 v[34:35], v[26:27]
	v_mov_b64_e32 v[32:33], v[24:25]
	v_mov_b64_e32 v[30:31], v[22:23]
	v_mov_b64_e32 v[28:29], v[20:21]
	v_mov_b32_e32 v35, v11
	v_mov_b64_e32 v[58:59], v[42:43]
	v_mov_b64_e32 v[54:55], v[38:39]
	v_mov_b64_e32 v[52:53], v[36:37]
	v_mov_b64_e32 v[56:57], v[40:41]
	v_mov_b64_e32 v[50:51], v[34:35]
	v_mov_b64_e32 v[48:49], v[32:33]
	v_mov_b64_e32 v[46:47], v[30:31]
	v_mov_b64_e32 v[44:45], v[28:29]
	v_mov_b32_e32 v52, v12
	v_mov_b32_e32 v53, v13
	v_mov_b32_e32 v54, v14
	v_mov_b32_e32 v55, v15
	v_mov_b64_e32 v[74:75], v[58:59]
	v_mov_b64_e32 v[72:73], v[56:57]
	v_mov_b64_e32 v[70:71], v[54:55]
	v_mov_b64_e32 v[68:69], v[52:53]
	v_mov_b64_e32 v[66:67], v[50:51]
	v_mov_b64_e32 v[64:65], v[48:49]
	v_mov_b64_e32 v[62:63], v[46:47]
	v_mov_b64_e32 v[60:61], v[44:45]
	v_mov_b32_e32 v72, v16
	v_mov_b32_e32 v73, v17
	v_mov_b32_e32 v74, v18
	s_andn2_b64 vcc, exec, s[14:15]
	v_mov_b32_e32 v75, v19
	s_cbranch_vccnz .LBB0_633
	v_lshlrev_b32_e32 v4, 2, v0
	v_add_u32_e32 v4, 0x1d000, v4
	ds_read_b32 v38, v4 offset:1024
	ds_read_b32 v39, v4 offset:1280
	ds_read_b32 v56, v4 offset:1536
	ds_read_b32 v57, v4 offset:1792
	v_cmp_eq_u32_e32 vcc, 0, v10
	s_waitcnt lgkmcnt(0)
	v_mul_f32_e32 v1, v39, v92
	v_fmac_f32_e32 v1, v38, v93
	v_fmac_f32_e32 v1, v56, v91
	v_fmac_f32_e32 v1, v57, v90
	v_mul_f32_e32 v2, 0xbfb8aa3b, v1
	v_exp_f32_e32 v2, v2
	s_nop 0
	v_add_f32_e32 v2, 1.0, v2
	v_rcp_f32_e32 v2, v2
	s_nop 0
	v_mul_f32_e32 v1, v1, v2
	v_mul_f32_e32 v2, v39, v91
	v_fmac_f32_e32 v2, v38, v92
	v_fmac_f32_e32 v2, v56, v90
	v_fmac_f32_e32 v2, v57, v89
	v_mul_f32_e32 v4, 0xbfb8aa3b, v2
	v_exp_f32_e32 v4, v4
	s_nop 0
	v_add_f32_e32 v4, 1.0, v4
	v_rcp_f32_e32 v4, v4
	s_nop 0
	v_mul_f32_e32 v2, v2, v4
	v_mul_f32_e32 v4, v39, v90
	v_fmac_f32_e32 v4, v38, v91
	v_fmac_f32_e32 v4, v56, v89
	v_fmac_f32_e32 v4, v57, v88
	v_mul_f32_e32 v5, 0xbfb8aa3b, v4
	v_exp_f32_e32 v5, v5
	s_nop 0
	v_add_f32_e32 v5, 1.0, v5
	v_rcp_f32_e32 v5, v5
	s_nop 0
	v_mul_f32_e32 v4, v4, v5
	v_mul_f32_e32 v5, v39, v89
	v_fmac_f32_e32 v5, v38, v90
	v_fmac_f32_e32 v5, v56, v88
	v_fmac_f32_e32 v5, v57, v87
	v_mul_f32_e32 v6, 0xbfb8aa3b, v5
	v_exp_f32_e32 v6, v6
	s_nop 0
	v_add_f32_e32 v6, 1.0, v6
	v_rcp_f32_e32 v6, v6
	s_nop 0
	v_mul_f32_e32 v5, v5, v6
	v_mul_f32_e32 v6, v39, v88
	v_fmac_f32_e32 v6, v38, v89
	v_fmac_f32_e32 v6, v56, v87
	v_fmac_f32_e32 v6, v57, v86
	v_mul_f32_e32 v7, 0xbfb8aa3b, v6
	v_exp_f32_e32 v7, v7
	s_nop 0
	v_add_f32_e32 v7, 1.0, v7
	v_rcp_f32_e32 v7, v7
	s_nop 0
	v_mul_f32_e32 v6, v6, v7
	v_mul_f32_e32 v7, v39, v87
	v_fmac_f32_e32 v7, v38, v88
	v_fmac_f32_e32 v7, v56, v86
	v_fmac_f32_e32 v7, v57, v85
	v_mul_f32_e32 v8, 0xbfb8aa3b, v7
	v_exp_f32_e32 v8, v8
	s_nop 0
	v_add_f32_e32 v8, 1.0, v8
	v_rcp_f32_e32 v8, v8
	s_nop 0
	v_mul_f32_e32 v7, v7, v8
	v_mul_f32_e32 v8, v39, v86
	v_fmac_f32_e32 v8, v38, v87
	v_fmac_f32_e32 v8, v56, v85
	v_fmac_f32_e32 v8, v57, v84
	v_mul_f32_e32 v36, 0xbfb8aa3b, v8
	v_exp_f32_e32 v36, v36
	s_nop 0
	v_add_f32_e32 v36, 1.0, v36
	v_rcp_f32_e32 v36, v36
	s_nop 0
	v_mul_f32_e32 v8, v8, v36
	v_mul_f32_e32 v36, v39, v85
	v_fmac_f32_e32 v36, v38, v86
	v_fmac_f32_e32 v36, v56, v84
	v_fmac_f32_e32 v36, v57, v83
	v_mul_f32_e32 v37, 0xbfb8aa3b, v36
	v_exp_f32_e32 v37, v37
	s_nop 0
	v_add_f32_e32 v37, 1.0, v37
	v_rcp_f32_e32 v37, v37
	s_nop 0
	v_mul_f32_e32 v36, v36, v37
	v_mul_f32_e32 v37, v39, v84
	v_fmac_f32_e32 v37, v38, v85
	v_fmac_f32_e32 v37, v56, v83
	v_fmac_f32_e32 v37, v57, v82
	v_mul_f32_e32 v58, 0xbfb8aa3b, v37
	v_exp_f32_e32 v58, v58
	s_nop 0
	v_add_f32_e32 v58, 1.0, v58
	v_rcp_f32_e32 v58, v58
	s_nop 0
	v_mul_f32_e32 v37, v37, v58
	v_mul_f32_e32 v58, v39, v83
	v_fmac_f32_e32 v58, v38, v84
	v_fmac_f32_e32 v58, v56, v82
	v_fmac_f32_e32 v58, v57, v81
	v_mul_f32_e32 v59, 0xbfb8aa3b, v58
	v_exp_f32_e32 v59, v59
	s_nop 0
	v_add_f32_e32 v59, 1.0, v59
	v_rcp_f32_e32 v59, v59
	s_nop 0
	v_mul_f32_e32 v84, v58, v59
	v_mul_f32_e32 v58, v39, v82
	v_fmac_f32_e32 v58, v38, v83
	v_fmac_f32_e32 v58, v56, v81
	v_fmac_f32_e32 v58, v57, v80
	v_mul_f32_e32 v59, 0xbfb8aa3b, v58
	v_exp_f32_e32 v59, v59
	v_mul_f32_e32 v85, v84, v84
	v_add_f32_e32 v59, 1.0, v59
	v_rcp_f32_e32 v59, v59
	s_nop 0
	v_mul_f32_e32 v83, v58, v59
	v_mul_f32_e32 v58, v39, v81
	v_fmac_f32_e32 v58, v38, v82
	v_fmac_f32_e32 v58, v56, v80
	v_fmac_f32_e32 v58, v57, v79
	v_mul_f32_e32 v59, 0xbfb8aa3b, v58
	v_exp_f32_e32 v59, v59
	v_mul_f32_e32 v86, v83, v83
	v_add_f32_e32 v59, 1.0, v59
	v_rcp_f32_e32 v59, v59
	s_nop 0
	v_mul_f32_e32 v82, v58, v59
	v_mul_f32_e32 v58, v39, v80
	v_fmac_f32_e32 v58, v38, v81
	v_fmac_f32_e32 v58, v56, v79
	v_fmac_f32_e32 v58, v57, v76
	v_mul_f32_e32 v59, 0xbfb8aa3b, v58
	v_exp_f32_e32 v59, v59
	v_mul_f32_e32 v87, v82, v82
	v_add_f32_e32 v59, 1.0, v59
	v_rcp_f32_e32 v59, v59
	s_nop 0
	v_mul_f32_e32 v81, v58, v59
	v_mul_f32_e32 v58, v39, v79
	v_fmac_f32_e32 v58, v38, v80
	v_fmac_f32_e32 v58, v56, v76
	v_fmac_f32_e32 v58, v57, v78
	v_mul_f32_e32 v59, 0xbfb8aa3b, v58
	v_exp_f32_e32 v59, v59
	v_mul_f32_e32 v80, v37, v37
	v_mul_f32_e32 v88, v81, v81
	v_add_f32_e32 v59, 1.0, v59
	v_rcp_f32_e32 v59, v59
	s_nop 0
	v_mul_f32_e32 v59, v58, v59
	v_mul_f32_e32 v58, v39, v76
	v_fmac_f32_e32 v58, v38, v79
	v_mul_f32_e32 v39, v39, v78
	v_fmac_f32_e32 v58, v56, v78
	v_fmac_f32_e32 v39, v38, v76
	v_fmac_f32_e32 v58, v57, v77
	v_fmac_f32_e32 v39, v56, v77
	v_mul_f32_e32 v79, 0xbfb8aa3b, v58
	v_fmac_f32_e32 v39, v57, v27
	v_exp_f32_e32 v79, v79
	v_mul_f32_e32 v27, 0xbfb8aa3b, v39
	v_exp_f32_e32 v27, v27
	v_mul_f32_e32 v38, v1, v1
	v_add_f32_e32 v79, 1.0, v79
	v_rcp_f32_e32 v79, v79
	v_add_f32_e32 v27, 1.0, v27
	v_rcp_f32_e32 v27, v27
	v_mul_f32_e32 v56, v4, v4
	v_mul_f32_e32 v58, v58, v79
	v_mul_f32_e32 v57, v5, v5
	v_mul_f32_e32 v27, v39, v27
	v_mul_f32_e32 v39, v2, v2
	v_mul_f32_e32 v76, v6, v6
	v_mul_f32_e32 v77, v7, v7
	v_mul_f32_e32 v78, v8, v8
	v_mul_f32_e32 v89, v59, v59
	v_mul_f32_e32 v90, v58, v58
	v_mul_f32_e32 v79, v36, v36
	v_mul_f32_e32 v91, v27, v27
	s_nop 1
	v_permlane32_swap_b32 v38, v80
	s_nop 1
	v_permlane32_swap_b32 v39, v85
	s_nop 1
	v_permlane32_swap_b32 v56, v86
	s_nop 1
	v_permlane32_swap_b32 v57, v87
	s_nop 1
	v_permlane32_swap_b32 v76, v88
	s_nop 1
	v_permlane32_swap_b32 v77, v89
	s_nop 1
	v_permlane32_swap_b32 v78, v90
	s_nop 0
	v_add_f32_e32 v38, v38, v80
	v_add_f32_e32 v39, v39, v85
	v_add_f32_e32 v56, v56, v86
	v_add_f32_e32 v76, v76, v88
	v_add_f32_e32 v77, v77, v89
	v_add_f32_e32 v78, v78, v90
	s_nop 1
	v_permlane32_swap_b32 v79, v91
	v_add_f32_e32 v57, v57, v87
	v_add_f32_e32 v79, v79, v91
	s_nop 1
	v_permlane16_swap_b32 v38, v76
	s_nop 1
	v_permlane16_swap_b32 v39, v77
	s_nop 1
	v_permlane16_swap_b32 v56, v78
	s_nop 1
	v_permlane16_swap_b32 v57, v79
	s_nop 0
	v_add_f32_e32 v38, v38, v76
	v_add_f32_e32 v56, v56, v78
	v_add_f32_e32 v39, v39, v77
	v_add_f32_e32 v57, v57, v79
	v_cndmask_b32_e32 v10, v38, v56, vcc
	v_cndmask_b32_e32 v38, v56, v38, vcc
	s_nop 1
	v_add_f32_dpp v10, v10, v38 quad_perm:[2,3,0,1] row_mask:0xf bank_mask:0xf bound_ctrl:1
	v_cndmask_b32_e32 v38, v39, v57, vcc
	v_cndmask_b32_e32 v39, v57, v39, vcc
	v_cmp_eq_u32_e32 vcc, 0, v9
	s_nop 0
	v_add_f32_dpp v38, v38, v39 quad_perm:[2,3,0,1] row_mask:0xf bank_mask:0xf bound_ctrl:1
	v_cndmask_b32_e32 v9, v10, v38, vcc
	v_cndmask_b32_e32 v10, v38, v10, vcc
	v_lshl_add_u32 v38, v0, 1, 0
	s_nop 0
	v_add_f32_dpp v9, v9, v10 quad_perm:[1,0,3,2] row_mask:0xf bank_mask:0xf bound_ctrl:1
	s_nop 1
	v_add_f32_dpp v9, v9, v9 row_ror:4 row_mask:0xf bank_mask:0xf bound_ctrl:1
	s_nop 1
	v_add_f32_dpp v10, v9, v9 row_ror:8 row_mask:0xf bank_mask:0xf bound_ctrl:1
	s_nop 0
	v_readlane_b32 s10, v10, 0
	s_nop 1
	v_add_f32_e32 v9, s10, v158
	v_cmp_gt_f32_e32 vcc, s75, v9
	v_mul_f32_e32 v39, 0x4b800000, v9
	v_readlane_b32 s10, v10, 1
	v_cndmask_b32_e32 v9, v9, v39, vcc
	v_rsq_f32_e32 v9, v9
	s_nop 0
	v_mul_f32_e32 v39, 0x45800000, v9
	v_cndmask_b32_e32 v9, v9, v39, vcc
	v_mul_f32_e32 v1, v1, v9
	v_cvt_pk_bf16_f32 v39, v1, s0
	v_add_u32_e32 v9, s38, v38
	ds_write_b16 v9, v39 offset:9216
	v_add_f32_e32 v39, s10, v158
	v_cmp_gt_f32_e32 vcc, s75, v39
	v_mul_f32_e32 v56, 0x4b800000, v39
	v_add_u32_e32 v38, s39, v38
	v_cndmask_b32_e32 v39, v39, v56, vcc
	v_rsq_f32_e32 v39, v39
	v_readlane_b32 s10, v10, 2
	v_mul_f32_e32 v56, 0x45800000, v39
	v_cndmask_b32_e32 v39, v39, v56, vcc
	v_mul_f32_e32 v2, v2, v39
	v_cvt_pk_bf16_f32 v39, v2, s0
	ds_write_b16 v38, v39 offset:9360
	v_add_f32_e32 v38, s10, v158
	v_cmp_gt_f32_e32 vcc, s75, v38
	v_mul_f32_e32 v39, 0x4b800000, v38
	v_readlane_b32 s10, v10, 3
	v_cndmask_b32_e32 v38, v38, v39, vcc
	v_rsq_f32_e32 v38, v38
	s_nop 0
	v_mul_f32_e32 v39, 0x45800000, v38
	v_cndmask_b32_e32 v38, v38, v39, vcc
	v_mul_f32_e32 v4, v4, v38
	v_cvt_pk_bf16_f32 v38, v4, s0
	ds_write_b16 v9, v38 offset:9504
	v_add_f32_e32 v38, s10, v158
	v_cmp_gt_f32_e32 vcc, s75, v38
	v_mul_f32_e32 v39, 0x4b800000, v38
	v_readlane_b32 s10, v10, 16
	v_cndmask_b32_e32 v38, v38, v39, vcc
	v_rsq_f32_e32 v38, v38
	s_nop 0
	v_mul_f32_e32 v39, 0x45800000, v38
	v_cndmask_b32_e32 v38, v38, v39, vcc
	v_mul_f32_e32 v5, v5, v38
	v_cvt_pk_bf16_f32 v38, v5, s0
	ds_write_b16 v9, v38 offset:9648
	v_add_f32_e32 v38, s10, v158
	v_cmp_gt_f32_e32 vcc, s75, v38
	v_mul_f32_e32 v39, 0x4b800000, v38
	v_readlane_b32 s10, v10, 17
	v_cndmask_b32_e32 v38, v38, v39, vcc
	v_rsq_f32_e32 v38, v38
	s_nop 0
	v_mul_f32_e32 v39, 0x45800000, v38
	v_cndmask_b32_e32 v38, v38, v39, vcc
	v_mul_f32_e32 v38, v6, v38
	v_cvt_pk_bf16_f32 v6, v38, s0
	ds_write_b16 v9, v6 offset:9792
	v_add_f32_e32 v6, s10, v158
	v_cmp_gt_f32_e32 vcc, s75, v6
	v_mul_f32_e32 v39, 0x4b800000, v6
	v_readlane_b32 s10, v10, 18
	v_cndmask_b32_e32 v6, v6, v39, vcc
	v_rsq_f32_e32 v6, v6
	s_nop 0
	v_mul_f32_e32 v39, 0x45800000, v6
	v_cndmask_b32_e32 v6, v6, v39, vcc
	v_mul_f32_e32 v39, v7, v6
	v_cvt_pk_bf16_f32 v6, v39, s0
	ds_write_b16 v9, v6 offset:9936
	v_add_f32_e32 v6, s10, v158
	v_cmp_gt_f32_e32 vcc, s75, v6
	v_mul_f32_e32 v7, 0x4b800000, v6
	v_readlane_b32 s10, v10, 19
	v_cndmask_b32_e32 v6, v6, v7, vcc
	v_rsq_f32_e32 v6, v6
	s_nop 0
	v_mul_f32_e32 v7, 0x45800000, v6
	v_cndmask_b32_e32 v6, v6, v7, vcc
	v_mul_f32_e32 v56, v8, v6
	v_cvt_pk_bf16_f32 v6, v56, s0
	ds_write_b16 v9, v6 offset:10080
	v_add_f32_e32 v6, s10, v158
	v_cmp_gt_f32_e32 vcc, s75, v6
	v_mul_f32_e32 v7, 0x4b800000, v6
	v_readlane_b32 s10, v10, 32
	v_cndmask_b32_e32 v6, v6, v7, vcc
	v_rsq_f32_e32 v6, v6
	v_cvt_pk_bf16_f32 v8, v38, v39
	v_mul_f32_e32 v7, 0x45800000, v6
	v_cndmask_b32_e32 v6, v6, v7, vcc
	v_mul_f32_e32 v36, v36, v6
	v_cvt_pk_bf16_f32 v6, v36, s0
	ds_write_b16 v9, v6 offset:10224
	v_add_f32_e32 v6, s10, v158
	v_cmp_gt_f32_e32 vcc, s75, v6
	v_mul_f32_e32 v7, 0x4b800000, v6
	v_readlane_b32 s10, v10, 33
	v_cndmask_b32_e32 v6, v6, v7, vcc
	v_rsq_f32_e32 v6, v6
	s_nop 0
	v_mul_f32_e32 v7, 0x45800000, v6
	v_cndmask_b32_e32 v6, v6, v7, vcc
	v_mul_f32_e32 v37, v37, v6
	v_cvt_pk_bf16_f32 v6, v37, s0
	ds_write_b16 v9, v6 offset:10368
	v_add_f32_e32 v6, s10, v158
	v_cmp_gt_f32_e32 vcc, s75, v6
	v_mul_f32_e32 v7, 0x4b800000, v6
	v_readlane_b32 s10, v10, 34
	v_cndmask_b32_e32 v6, v6, v7, vcc
	v_rsq_f32_e32 v6, v6
	s_nop 0
	v_mul_f32_e32 v7, 0x45800000, v6
	v_cndmask_b32_e32 v6, v6, v7, vcc
	v_mul_f32_e32 v57, v84, v6
	v_cvt_pk_bf16_f32 v6, v57, s0
	ds_write_b16 v9, v6 offset:10512
	v_add_f32_e32 v6, s10, v158
	v_cmp_gt_f32_e32 vcc, s75, v6
	v_mul_f32_e32 v7, 0x4b800000, v6
	v_readlane_b32 s10, v10, 35
	v_cndmask_b32_e32 v6, v6, v7, vcc
	v_rsq_f32_e32 v6, v6
	s_nop 0
	v_mul_f32_e32 v7, 0x45800000, v6
	v_cndmask_b32_e32 v6, v6, v7, vcc
	v_mul_f32_e32 v76, v83, v6
	v_cvt_pk_bf16_f32 v6, v76, s0
	ds_write_b16 v9, v6 offset:10656
	v_add_f32_e32 v6, s10, v158
	v_cmp_gt_f32_e32 vcc, s75, v6
	v_mul_f32_e32 v7, 0x4b800000, v6
	v_readlane_b32 s10, v10, 48
	v_cndmask_b32_e32 v6, v6, v7, vcc
	v_rsq_f32_e32 v6, v6
	s_nop 0
	v_mul_f32_e32 v7, 0x45800000, v6
	v_cndmask_b32_e32 v6, v6, v7, vcc
	v_mul_f32_e32 v77, v82, v6
	v_cvt_pk_bf16_f32 v6, v77, s0
	ds_write_b16 v9, v6 offset:10800
	v_add_f32_e32 v6, s10, v158
	v_cmp_gt_f32_e32 vcc, s75, v6
	v_mul_f32_e32 v7, 0x4b800000, v6
	v_readlane_b32 s10, v10, 49
	v_cndmask_b32_e32 v6, v6, v7, vcc
	v_rsq_f32_e32 v6, v6
	s_nop 0
	v_mul_f32_e32 v7, 0x45800000, v6
	v_cndmask_b32_e32 v6, v6, v7, vcc
	v_mul_f32_e32 v78, v81, v6
	v_cvt_pk_bf16_f32 v6, v78, s0
	ds_write_b16 v9, v6 offset:10944
	v_add_f32_e32 v6, s10, v158
	v_cmp_gt_f32_e32 vcc, s75, v6
	v_mul_f32_e32 v7, 0x4b800000, v6
	v_readlane_b32 s10, v10, 50
	v_cndmask_b32_e32 v6, v6, v7, vcc
	v_rsq_f32_e32 v6, v6
	s_nop 0
	v_mul_f32_e32 v7, 0x45800000, v6
	v_cndmask_b32_e32 v6, v6, v7, vcc
	v_mul_f32_e32 v59, v59, v6
	v_cvt_pk_bf16_f32 v6, v59, s0
	ds_write_b16 v9, v6 offset:11088
	v_add_f32_e32 v6, s10, v158
	v_cmp_gt_f32_e32 vcc, s75, v6
	v_mul_f32_e32 v7, 0x4b800000, v6
	v_readlane_b32 s10, v10, 51
	v_cndmask_b32_e32 v6, v6, v7, vcc
	v_rsq_f32_e32 v6, v6
	v_cvt_pk_bf16_f32 v38, v78, v59
	v_mul_f32_e32 v7, 0x45800000, v6
	v_cndmask_b32_e32 v6, v6, v7, vcc
	v_mul_f32_e32 v58, v58, v6
	v_cvt_pk_bf16_f32 v6, v58, s0
	ds_write_b16 v9, v6 offset:11232
	v_add_f32_e32 v6, s10, v158
	v_cmp_gt_f32_e32 vcc, s75, v6
	v_mul_f32_e32 v7, 0x4b800000, v6
	s_nop 0
	v_cndmask_b32_e32 v6, v6, v7, vcc
	v_rsq_f32_e32 v6, v6
	s_nop 0
	v_mul_f32_e32 v7, 0x45800000, v6
	v_cndmask_b32_e32 v6, v6, v7, vcc
	v_mul_f32_e32 v10, v27, v6
	v_cvt_pk_bf16_f32 v6, v10, s0
	ds_write_b16 v9, v6 offset:11376
	v_mul_lo_u32 v6, v0, s89
	v_add_u32_e32 v27, s66, v6
	v_cvt_pk_bf16_f32 v6, v1, v2
	v_cvt_pk_bf16_f32 v7, v4, v5
	v_cvt_pk_bf16_f32 v9, v56, v36
	s_andn2_b64 vcc, exec, s[28:29]
	v_cvt_pk_bf16_f32 v36, v37, v57
	v_cvt_pk_bf16_f32 v37, v76, v77
	v_cvt_pk_bf16_f32 v39, v58, v10
	ds_write_b128 v27, v[6:9] offset:18432
	ds_write_b128 v27, v[36:39] offset:18448
	s_cbranch_vccnz .LBB0_631
	v_lshlrev_b32_e32 v1, 16, v185
	v_add_f32_e32 v1, v169, v1
	s_mov_b32 s10, 0x41a00000
	v_cmp_nlt_f32_e32 vcc, s10, v1
	s_and_saveexec_b64 s[10:11], vcc
	s_cbranch_execz .LBB0_630
	v_mul_f32_e32 v1, 0x3fb8aa3b, v1
	v_exp_f32_e32 v1, v1
	s_mov_b32 s12, 0x3f2aaaab
	v_add_f32_e32 v2, 1.0, v1
	v_frexp_mant_f32_e32 v7, v2
	v_cvt_f64_f32_e32 v[4:5], v2
	v_add_f32_e32 v6, -1.0, v2
	v_frexp_exp_i32_f64_e32 v4, v[4:5]
	v_cmp_gt_f32_e32 vcc, s12, v7
	v_sub_f32_e32 v8, v6, v2
	v_sub_f32_e32 v6, v1, v6
	v_subbrev_co_u32_e32 v10, vcc, 0, v4, vcc
	v_add_f32_e32 v8, 1.0, v8
	v_sub_u32_e32 v4, 0, v10
	v_add_f32_e32 v6, v6, v8
	v_ldexp_f32 v2, v2, v4
	v_ldexp_f32 v4, v6, v4
	v_add_f32_e32 v6, -1.0, v2
	v_add_f32_e32 v5, 1.0, v6
	v_sub_f32_e32 v5, v2, v5
	v_add_f32_e32 v7, v4, v5
	v_add_f32_e32 v5, 1.0, v2
	v_add_f32_e32 v8, -1.0, v5
	v_sub_f32_e32 v2, v2, v8
	v_add_f32_e32 v2, v4, v2
	v_add_f32_e32 v27, v5, v2
	v_rcp_f32_e32 v38, v27
	v_sub_f32_e32 v4, v27, v5
	v_add_f32_e32 v5, v6, v7
	v_sub_f32_e32 v2, v2, v4
	v_mul_f32_e32 v56, v5, v38
	v_sub_f32_e32 v4, v5, v6
	v_mul_f32_e32 v6, v27, v56
	v_fma_f32 v8, v56, v27, -v6
	v_fmac_f32_e32 v8, v56, v2
	v_sub_f32_e32 v39, v7, v4
	v_add_f32_e32 v4, v6, v8
	v_sub_f32_e32 v7, v5, v4
	v_pk_add_f32 v[36:37], v[4:5], v[6:7] neg_lo:[0,1] neg_hi:[0,1]
	v_mov_b32_e32 v9, v4
	v_pk_add_f32 v[4:5], v[36:37], v[8:9] neg_lo:[0,1] neg_hi:[0,1]
	s_mov_b32 s12, 0x3f317218
	v_add_f32_e32 v5, v39, v5
	v_add_f32_e32 v4, v4, v5
	v_add_f32_e32 v5, v7, v4
	v_mul_f32_e32 v39, v38, v5
	v_mul_f32_e32 v6, v27, v39
	v_fma_f32 v8, v39, v27, -v6
	v_fmac_f32_e32 v8, v39, v2
	v_sub_f32_e32 v2, v7, v5
	v_add_f32_e32 v2, v4, v2
	v_add_f32_e32 v4, v6, v8
	v_sub_f32_e32 v7, v5, v4
	v_pk_add_f32 v[36:37], v[4:5], v[6:7] neg_lo:[0,1] neg_hi:[0,1]
	v_mov_b32_e32 v9, v4
	v_pk_add_f32 v[4:5], v[36:37], v[8:9] neg_lo:[0,1] neg_hi:[0,1]
	v_cmp_neq_f32_e32 vcc, s70, v1
	v_add_f32_e32 v2, v2, v5
	v_add_f32_e32 v2, v4, v2
	v_add_f32_e32 v5, v56, v39
	v_add_f32_e32 v2, v7, v2
	v_sub_f32_e32 v4, v5, v56
	v_mul_f32_e32 v2, v38, v2
	v_sub_f32_e32 v4, v39, v4
	v_add_f32_e32 v2, v4, v2
	v_add_f32_e32 v6, v5, v2
	v_mul_f32_e32 v8, v6, v6
	v_fmamk_f32 v4, v8, 0x3e9b6dac, v231
	v_fmaak_f32 v161, v8, v4, 0x3f2aaada
	v_cvt_f32_i32_e32 v4, v10
	v_sub_f32_e32 v5, v6, v5
	v_sub_f32_e32 v2, v2, v5
	v_mul_f32_e32 v5, v6, v8
	v_pk_mul_f32 v[8:9], v[4:5], v[160:161]
	v_ldexp_f32 v7, v6, 1
	v_fma_f32 v6, v4, s12, -v8
	v_fmac_f32_e32 v6, 0xb102e308, v4
	v_pk_add_f32 v[4:5], v[8:9], v[6:7]
	v_ldexp_f32 v2, v2, 1
	v_sub_f32_e32 v7, v5, v7
	v_sub_f32_e32 v7, v9, v7
	v_add_f32_e32 v37, v2, v7
	v_mov_b32_e32 v36, v8
	v_pk_add_f32 v[8:9], v[4:5], v[8:9] neg_lo:[0,1] neg_hi:[0,1]
	v_pk_add_f32 v[38:39], v[4:5], v[36:37]
	v_mov_b32_e32 v7, v4
	v_mov_b32_e32 v9, v39
	v_pk_add_f32 v[56:57], v[6:7], v[8:9] neg_lo:[0,1] neg_hi:[0,1]
	v_pk_add_f32 v[6:7], v[6:7], v[8:9]
	v_mov_b32_e32 v36, v37
	v_pk_add_f32 v[8:9], v[6:7], v[4:5] op_sel:[1,0] op_sel_hi:[0,1] neg_lo:[0,1] neg_hi:[0,1]
	v_pk_add_f32 v[58:59], v[38:39], v[8:9] op_sel_hi:[1,0] neg_lo:[0,1] neg_hi:[0,1]
	v_mov_b32_e32 v38, v39
	v_mov_b32_e32 v39, v7
	v_pk_mov_b32 v[8:9], v[4:5], v[8:9] op_sel:[1,0]
	v_mov_b32_e32 v37, v4
	v_pk_add_f32 v[8:9], v[38:39], v[8:9] neg_lo:[0,1] neg_hi:[0,1]
	v_mov_b32_e32 v58, v56
	v_pk_add_f32 v[4:5], v[36:37], v[8:9] neg_lo:[0,1] neg_hi:[0,1]
	v_mov_b32_e32 v57, v7
	v_pk_add_f32 v[8:9], v[58:59], v[4:5]
	s_mov_b32 s12, 0x33800000
	v_pk_add_f32 v[36:37], v[8:9], v[8:9] op_sel:[0,1] op_sel_hi:[1,0]
	s_nop 0
	v_pk_add_f32 v[6:7], v[6:7], v[36:37] op_sel:[1,0] op_sel_hi:[0,1]
	v_mov_b32_e32 v9, v6
	v_pk_add_f32 v[38:39], v[8:9], v[56:57] neg_lo:[0,1] neg_hi:[0,1]
	v_mov_b32_e32 v5, v36
	v_sub_f32_e32 v2, v8, v38
	v_pk_add_f32 v[4:5], v[4:5], v[38:39] neg_lo:[0,1] neg_hi:[0,1]
	v_sub_f32_e32 v2, v56, v2
	v_add_f32_e32 v2, v4, v2
	v_add_f32_e32 v2, v2, v5
	v_add_f32_e32 v2, v6, v2
	v_cndmask_b32_e32 v2, v236, v2, vcc
	v_cmp_ngt_f32_e32 vcc, -1.0, v1
	s_nop 1
	v_cndmask_b32_e32 v2, v237, v2, vcc
	v_cmp_neq_f32_e32 vcc, -1.0, v1
	s_nop 1
	v_cndmask_b32_e32 v2, v238, v2, vcc
	v_cmp_lt_f32_e64 vcc, |v1|, s12
	s_nop 1
	v_cndmask_b32_e32 v1, v2, v1, vcc

.LBB0_960:
	v_mov_b32_e32 v2, s69
	s_waitcnt lgkmcnt(0)
	s_barrier
	ds_read_b32 v2, v2
	s_mov_b64 s[6:7], -1
	s_waitcnt lgkmcnt(0)
	v_readfirstlane_b32 s27, v2
	s_cmpk_gt_i32 s27, 0x1ef
	s_cbranch_scc1 .LBB0_953
	s_cmpk_gt_u32 s27, 63
	s_cbranch_scc1 .Lqo_0
	s_addk_i32 s27, 176
	s_branch .Lqo_done
.Lqo_0:
	s_cmpk_gt_u32 s27, 239
	s_cbranch_scc1 .Lqo_1
	s_sub_i32 s27, s27, 64
	s_branch .Lqo_done
.Lqo_1:
	s_cmpk_gt_u32 s27, 367
	s_cbranch_scc1 .Lqo_2
	s_branch .Lqo_done
.Lqo_2:
.Lqo_done:
	s_cmpk_lt_i32 s27, 0xb0
	s_cselect_b64 s[6:7], -1, 0
	s_cmpk_lt_u32 s27, 0x170
	s_cselect_b32 s22, 2, 1
	s_cmpk_gt_u32 s27, 0xef
	s_cselect_b64 s[24:25], -1, 0
	s_and_b64 s[20:21], s[24:25], exec
	s_cselect_b32 s21, s22, 0
	s_mov_b64 s[30:31], -1
	s_and_b64 vcc, exec, s[6:7]
	s_cbranch_vccnz .LBB0_964
	s_and_b64 s[22:23], s[24:25], exec
	s_cselect_b32 s26, 8, 4
	s_add_i32 s20, s27, 0xffffff10
	s_cmpk_lt_u32 s20, 0x80
	s_movk_i32 s20, 0xfe90
	s_cselect_b32 s20, 0xffffff10, s20
	s_and_b64 s[22:23], s[24:25], exec
	s_cselect_b32 s20, s20, 0xffffff50
	s_add_i32 s28, s20, s27
	s_lshl_b32 s20, s26, 1
	s_sext_i32_i16 s22, s28
	v_cvt_f32_ubyte0_e32 v4, s20
	v_cvt_f32_i32_e32 v2, s22
	v_rcp_iflag_f32_e32 v5, v4
	s_ashr_i32 s20, s22, 30
	s_or_b32 s20, s20, 1
	v_mul_f32_e32 v5, v2, v5
	v_trunc_f32_e32 v5, v5
	v_fma_f32 v2, -v5, v4, v2
	v_cvt_i32_f32_e32 v5, v5
	v_cmp_ge_f32_e64 s[22:23], |v2|, v4
	s_and_b64 s[22:23], s[22:23], exec
	s_cselect_b32 s20, s20, 0
	v_readfirstlane_b32 s22, v5
	s_add_i32 s22, s22, s20
	s_sext_i32_i16 s20, s22
	s_lshl_b32 s29, s20, 1
	s_and_b64 s[22:23], s[24:25], exec
	s_cselect_b32 s30, 3, 2
	s_lshl_b32 s22, s29, s30
	s_sub_i32 s28, s28, s22
	s_sext_i32_i16 s22, s28
	v_cvt_f32_ubyte0_e32 v4, s26
	v_cvt_f32_i32_e32 v2, s22
	v_rcp_iflag_f32_e32 v5, v4
	s_ashr_i32 s22, s22, 30
	s_or_b32 s26, s22, 1
	v_mul_f32_e32 v5, v2, v5
	v_trunc_f32_e32 v5, v5
	v_fma_f32 v2, -v5, v4, v2
	v_cvt_i32_f32_e32 v5, v5
	v_cmp_ge_f32_e64 s[22:23], |v2|, v4
	s_and_b64 s[22:23], s[22:23], exec
	s_cselect_b32 s22, s26, 0
	v_readfirstlane_b32 s23, v5
	s_add_i32 s23, s23, s22
	s_sext_i32_i16 s56, s23
	s_lshl_b32 s22, s56, s30
	s_sub_i32 s26, s28, s22
	s_and_b64 s[22:23], s[24:25], exec
	s_cselect_b32 s22, 1, 2
	s_lshl_b32 s23, s20, 5
	s_lshl_b32 s25, s21, 8
	s_lshl_b32 s24, s56, 4
	s_add_i32 s23, s23, s25
	s_lshl_b32 s22, s26, s22
	s_add_i32 s23, s23, s24
	s_add_i32 s26, s23, 32
	s_add_i32 s28, s23, 40
	s_add_i32 s54, s22, 16
	s_mov_b32 s23, 2
	s_cbranch_execz .LBB0_965
